# weight transpose-convert: 16 tile loads issued together (16 loops); diff near-path branch-free bias lookup
# speedup vs baseline: 1.0421x; 1.0198x over previous
;     ...
;   for (int t = blockIdx.x; t < ntiles; t += gridDim.x) {
;     const int kt = t % nkt, nt = t / nkt;
;     __syncthreads();
; #pragma unroll 4
;     for (int i = 0; i < 16; ++i) {
;       int e = tid + 256 * i, r = e >> 6, c = e & 63;
;       int n = nt * 64 + c;
;       int sc = remap ? colmap_in(n) : n;
;       float v = sc >= 0 ? src[(size_t)(kt * 64 + r) * Nsrc + sc] : 0.f;
;       tile[r * 65 + c] = v;
;     }
.LBB0_16:
	v_add_u32_e32 v4, s23, v1
	v_ashrrev_i32_e32 v20, 6, v4
	v_mov_b32_e32 v19, 0
	v_mov_b32_e32 v21, 0
	s_and_saveexec_b64 s[0:1], vcc
	s_cbranch_execz .LBB0_18
	v_add_u32_e32 v21, s22, v20
	v_mad_i64_i32 v[22:23], s[24:25], v21, s18, v[12:13]
	s_and_b32 s32, s23, 0xfff
	s_cbranch_scc1 .Ltc_skip16
	s_lshl_b32 s100, s18, 2
	s_mov_b32 s101, 0
	v_mov_b64_e32 v[116:117], v[22:23]
	global_load_dword v100, v[116:117], off
	v_lshl_add_u64 v[116:117], v[116:117], 0, s[100:101]
	global_load_dword v101, v[116:117], off
	v_lshl_add_u64 v[116:117], v[116:117], 0, s[100:101]
	global_load_dword v102, v[116:117], off
	v_lshl_add_u64 v[116:117], v[116:117], 0, s[100:101]
	global_load_dword v103, v[116:117], off
	v_lshl_add_u64 v[116:117], v[116:117], 0, s[100:101]
	global_load_dword v104, v[116:117], off
	v_lshl_add_u64 v[116:117], v[116:117], 0, s[100:101]
	global_load_dword v105, v[116:117], off
	v_lshl_add_u64 v[116:117], v[116:117], 0, s[100:101]
	global_load_dword v106, v[116:117], off
	v_lshl_add_u64 v[116:117], v[116:117], 0, s[100:101]
	global_load_dword v107, v[116:117], off
	v_lshl_add_u64 v[116:117], v[116:117], 0, s[100:101]
	global_load_dword v108, v[116:117], off
	v_lshl_add_u64 v[116:117], v[116:117], 0, s[100:101]
	global_load_dword v109, v[116:117], off
	v_lshl_add_u64 v[116:117], v[116:117], 0, s[100:101]
	global_load_dword v110, v[116:117], off
	v_lshl_add_u64 v[116:117], v[116:117], 0, s[100:101]
	global_load_dword v111, v[116:117], off
	v_lshl_add_u64 v[116:117], v[116:117], 0, s[100:101]
	global_load_dword v112, v[116:117], off
	v_lshl_add_u64 v[116:117], v[116:117], 0, s[100:101]
	global_load_dword v113, v[116:117], off
	v_lshl_add_u64 v[116:117], v[116:117], 0, s[100:101]
	global_load_dword v114, v[116:117], off
	v_lshl_add_u64 v[116:117], v[116:117], 0, s[100:101]
	global_load_dword v115, v[116:117], off
	s_waitcnt vmcnt(0)
.Ltc_skip16:
	v_mov_b32_e32 v21, v100
.LBB0_18:
	s_or_b64 exec, exec, s[0:1]
	v_mad_u64_u32 v[22:23], s[0:1], v20, s19, v[2:3]
	v_add_u32_e32 v20, 0x100, v4
	v_ashrrev_i32_e32 v20, 6, v20
	s_waitcnt vmcnt(0)
	ds_write_b32 v22, v21
	s_and_saveexec_b64 s[0:1], vcc
	s_cbranch_execz .LBB0_20
	v_add_u32_e32 v19, s22, v20
	v_mad_i64_i32 v[22:23], s[24:25], v19, s18, v[12:13]
	v_mov_b32_e32 v19, v101
.LBB0_20:
	s_or_b64 exec, exec, s[0:1]
	v_mad_u64_u32 v[20:21], s[0:1], v20, s19, v[2:3]
	s_waitcnt vmcnt(0)
	ds_write_b32 v20, v19
	v_add_u32_e32 v19, 0x200, v4
	v_ashrrev_i32_e32 v20, 6, v19
	v_mov_b32_e32 v19, 0
	v_mov_b32_e32 v21, 0
	s_and_saveexec_b64 s[0:1], vcc
	s_cbranch_execz .LBB0_22
	v_add_u32_e32 v21, s22, v20
	v_mad_i64_i32 v[22:23], s[24:25], v21, s18, v[12:13]
	v_mov_b32_e32 v21, v102
.LBB0_22:
	s_or_b64 exec, exec, s[0:1]
	v_add_u32_e32 v4, 0x300, v4
	v_mad_u64_u32 v[22:23], s[0:1], v20, s19, v[2:3]
	v_ashrrev_i32_e32 v4, 6, v4
	s_waitcnt vmcnt(0)
	ds_write_b32 v22, v21
	s_and_saveexec_b64 s[0:1], vcc
	s_cbranch_execz .LBB0_15
	v_add_u32_e32 v19, s22, v4
	v_mad_i64_i32 v[20:21], s[24:25], v19, s18, v[12:13]
	v_mov_b32_e32 v19, v103
	v_mov_b32_e32 v100, v104
	v_mov_b32_e32 v101, v105
	v_mov_b32_e32 v102, v106
	v_mov_b32_e32 v103, v107
	v_mov_b32_e32 v104, v108
	v_mov_b32_e32 v105, v109
	v_mov_b32_e32 v106, v110
	v_mov_b32_e32 v107, v111
	v_mov_b32_e32 v108, v112
	v_mov_b32_e32 v109, v113
	v_mov_b32_e32 v110, v114
	v_mov_b32_e32 v111, v115
	s_branch .LBB0_15

;     ...
;     for (int i = 0; i < 16; ++i) {
;       int e = tid + 256 * i, r = e >> 6, c = e & 63;
;       int n = nt * 64 + c;
;       int sc = remap ? colmap_in(n) : n;
;       float v = sc >= 0 ? src[(size_t)(kt * 64 + r) * Nsrc + sc] : 0.f;
.LBB0_29:
	v_add_u32_e32 v4, s20, v1
	v_ashrrev_i32_e32 v20, 6, v4
	v_mov_b32_e32 v19, 0
	s_and_b64 vcc, exec, s[0:1]
	v_mov_b32_e32 v21, 0
	s_cbranch_vccnz .LBB0_31
	v_add_u32_e32 v22, s19, v20
	v_ashrrev_i32_e32 v23, 31, v22
	v_lshlrev_b64 v[22:23], 12, v[22:23]
	v_lshl_add_u64 v[22:23], v[12:13], 0, v[22:23]
	s_and_b32 s32, s20, 0xfff
	s_cbranch_scc1 .Ltc_skip15
	s_mov_b64 s[100:101], 0x4000
	v_mov_b64_e32 v[116:117], v[22:23]
	global_load_dword v100, v[116:117], off
	v_lshl_add_u64 v[116:117], v[116:117], 0, s[100:101]
	global_load_dword v101, v[116:117], off
	v_lshl_add_u64 v[116:117], v[116:117], 0, s[100:101]
	global_load_dword v102, v[116:117], off
	v_lshl_add_u64 v[116:117], v[116:117], 0, s[100:101]
	global_load_dword v103, v[116:117], off
	v_lshl_add_u64 v[116:117], v[116:117], 0, s[100:101]
	global_load_dword v104, v[116:117], off
	v_lshl_add_u64 v[116:117], v[116:117], 0, s[100:101]
	global_load_dword v105, v[116:117], off
	v_lshl_add_u64 v[116:117], v[116:117], 0, s[100:101]
	global_load_dword v106, v[116:117], off
	v_lshl_add_u64 v[116:117], v[116:117], 0, s[100:101]
	global_load_dword v107, v[116:117], off
	v_lshl_add_u64 v[116:117], v[116:117], 0, s[100:101]
	global_load_dword v108, v[116:117], off
	v_lshl_add_u64 v[116:117], v[116:117], 0, s[100:101]
	global_load_dword v109, v[116:117], off
	v_lshl_add_u64 v[116:117], v[116:117], 0, s[100:101]
	global_load_dword v110, v[116:117], off
	v_lshl_add_u64 v[116:117], v[116:117], 0, s[100:101]
	global_load_dword v111, v[116:117], off
	v_lshl_add_u64 v[116:117], v[116:117], 0, s[100:101]
	global_load_dword v112, v[116:117], off
	v_lshl_add_u64 v[116:117], v[116:117], 0, s[100:101]
	global_load_dword v113, v[116:117], off
	v_lshl_add_u64 v[116:117], v[116:117], 0, s[100:101]
	global_load_dword v114, v[116:117], off
	v_lshl_add_u64 v[116:117], v[116:117], 0, s[100:101]
	global_load_dword v115, v[116:117], off
	s_waitcnt vmcnt(0)

;     ...
;     for (int i = 0; i < 16; ++i) {
;       int e = tid + 256 * i, r = e >> 6, c = e & 63;
;       int n = nt * 64 + c;
;       int sc = remap ? colmap_in(n) : n;
;       float v = sc >= 0 ? src[(size_t)(kt * 64 + r) * Nsrc + sc] : 0.f;
;       tile[r * 65 + c] = v;
;     }
.LBB0_31:
	v_mad_u64_u32 v[22:23], s[22:23], v20, s3, v[2:3]
	v_add_u32_e32 v20, 0x100, v4
	s_and_b64 vcc, exec, s[0:1]
	v_ashrrev_i32_e32 v20, 6, v20
	s_waitcnt vmcnt(0)
	ds_write_b32 v22, v21
	s_cbranch_vccnz .LBB0_33
	v_add_u32_e32 v22, s19, v20
	v_ashrrev_i32_e32 v23, 31, v22
	v_lshlrev_b64 v[22:23], 12, v[22:23]
	v_lshl_add_u64 v[22:23], v[12:13], 0, v[22:23]
	v_mov_b32_e32 v19, v101
.LBB0_33:
	v_mad_u64_u32 v[20:21], s[22:23], v20, s3, v[2:3]
	s_waitcnt vmcnt(0)
	ds_write_b32 v20, v19
	v_add_u32_e32 v19, 0x200, v4
	v_ashrrev_i32_e32 v20, 6, v19
	v_mov_b32_e32 v19, 0
	s_and_b64 vcc, exec, s[0:1]
	v_mov_b32_e32 v21, 0
	s_cbranch_vccnz .LBB0_35
	v_add_u32_e32 v22, s19, v20
	v_ashrrev_i32_e32 v23, 31, v22
	v_lshlrev_b64 v[22:23], 12, v[22:23]
	v_lshl_add_u64 v[22:23], v[12:13], 0, v[22:23]
	v_mov_b32_e32 v21, v102
.LBB0_35:
	v_add_u32_e32 v4, 0x300, v4
	v_mad_u64_u32 v[22:23], s[22:23], v20, s3, v[2:3]
	s_and_b64 vcc, exec, s[0:1]
	v_ashrrev_i32_e32 v4, 6, v4
	s_waitcnt vmcnt(0)
	ds_write_b32 v22, v21
	s_cbranch_vccnz .LBB0_28
	v_add_u32_e32 v20, s19, v4
	v_ashrrev_i32_e32 v21, 31, v20
	v_lshlrev_b64 v[20:21], 12, v[20:21]
	v_lshl_add_u64 v[20:21], v[12:13], 0, v[20:21]
	v_mov_b32_e32 v19, v103
	v_mov_b32_e32 v100, v104
	v_mov_b32_e32 v101, v105
	v_mov_b32_e32 v102, v106
	v_mov_b32_e32 v103, v107
	v_mov_b32_e32 v104, v108
	v_mov_b32_e32 v105, v109
	v_mov_b32_e32 v106, v110
	v_mov_b32_e32 v107, v111
	v_mov_b32_e32 v108, v112
	v_mov_b32_e32 v109, v113
	v_mov_b32_e32 v110, v114
	v_mov_b32_e32 v111, v115
	s_branch .LBB0_28

;     ...
;     for (int i = 0; i < 16; ++i) {
;       int e = tid + 256 * i, r = e >> 6, c = e & 63;
;       int n = nt * 64 + c;
;       int sc = remap ? colmap_in(n) : n;
;       float v = sc >= 0 ? src[(size_t)(kt * 64 + r) * Nsrc + sc] : 0.f;
.LBB0_42:
	v_add_u32_e32 v4, s18, v1
	v_ashrrev_i32_e32 v20, 6, v4
	v_mov_b32_e32 v19, 0
	s_and_b64 vcc, exec, s[0:1]
	v_mov_b32_e32 v21, 0
	s_cbranch_vccnz .LBB0_44
	v_add_u32_e32 v22, s17, v20
	v_ashrrev_i32_e32 v23, 31, v22
	v_lshlrev_b64 v[22:23], 12, v[22:23]
	v_lshl_add_u64 v[22:23], v[12:13], 0, v[22:23]
	s_and_b32 s32, s18, 0xfff
	s_cbranch_scc1 .Ltc_skip14
	s_mov_b64 s[100:101], 0x4000
	v_mov_b64_e32 v[116:117], v[22:23]
	global_load_dword v100, v[116:117], off
	v_lshl_add_u64 v[116:117], v[116:117], 0, s[100:101]
	global_load_dword v101, v[116:117], off
	v_lshl_add_u64 v[116:117], v[116:117], 0, s[100:101]
	global_load_dword v102, v[116:117], off
	v_lshl_add_u64 v[116:117], v[116:117], 0, s[100:101]
	global_load_dword v103, v[116:117], off
	v_lshl_add_u64 v[116:117], v[116:117], 0, s[100:101]
	global_load_dword v104, v[116:117], off
	v_lshl_add_u64 v[116:117], v[116:117], 0, s[100:101]
	global_load_dword v105, v[116:117], off
	v_lshl_add_u64 v[116:117], v[116:117], 0, s[100:101]
	global_load_dword v106, v[116:117], off
	v_lshl_add_u64 v[116:117], v[116:117], 0, s[100:101]
	global_load_dword v107, v[116:117], off
	v_lshl_add_u64 v[116:117], v[116:117], 0, s[100:101]
	global_load_dword v108, v[116:117], off
	v_lshl_add_u64 v[116:117], v[116:117], 0, s[100:101]
	global_load_dword v109, v[116:117], off
	v_lshl_add_u64 v[116:117], v[116:117], 0, s[100:101]
	global_load_dword v110, v[116:117], off
	v_lshl_add_u64 v[116:117], v[116:117], 0, s[100:101]
	global_load_dword v111, v[116:117], off
	v_lshl_add_u64 v[116:117], v[116:117], 0, s[100:101]
	global_load_dword v112, v[116:117], off
	v_lshl_add_u64 v[116:117], v[116:117], 0, s[100:101]
	global_load_dword v113, v[116:117], off
	v_lshl_add_u64 v[116:117], v[116:117], 0, s[100:101]
	global_load_dword v114, v[116:117], off
	v_lshl_add_u64 v[116:117], v[116:117], 0, s[100:101]
	global_load_dword v115, v[116:117], off
	s_waitcnt vmcnt(0)

;     ...
;     for (int i = 0; i < 16; ++i) {
;       int e = tid + 256 * i, r = e >> 6, c = e & 63;
;       int n = nt * 64 + c;
;       int sc = remap ? colmap_in(n) : n;
;       float v = sc >= 0 ? src[(size_t)(kt * 64 + r) * Nsrc + sc] : 0.f;
;       tile[r * 65 + c] = v;
;     }
.LBB0_44:
	v_mad_u64_u32 v[22:23], s[20:21], v20, s3, v[2:3]
	v_add_u32_e32 v20, 0x100, v4
	s_and_b64 vcc, exec, s[0:1]
	v_ashrrev_i32_e32 v20, 6, v20
	s_waitcnt vmcnt(0)
	ds_write_b32 v22, v21
	s_cbranch_vccnz .LBB0_46
	v_add_u32_e32 v22, s17, v20
	v_ashrrev_i32_e32 v23, 31, v22
	v_lshlrev_b64 v[22:23], 12, v[22:23]
	v_lshl_add_u64 v[22:23], v[12:13], 0, v[22:23]
	v_mov_b32_e32 v19, v101
.LBB0_46:
	v_mad_u64_u32 v[20:21], s[20:21], v20, s3, v[2:3]
	s_waitcnt vmcnt(0)
	ds_write_b32 v20, v19
	v_add_u32_e32 v19, 0x200, v4
	v_ashrrev_i32_e32 v20, 6, v19
	v_mov_b32_e32 v19, 0
	s_and_b64 vcc, exec, s[0:1]
	v_mov_b32_e32 v21, 0
	s_cbranch_vccnz .LBB0_48
	v_add_u32_e32 v22, s17, v20
	v_ashrrev_i32_e32 v23, 31, v22
	v_lshlrev_b64 v[22:23], 12, v[22:23]
	v_lshl_add_u64 v[22:23], v[12:13], 0, v[22:23]
	v_mov_b32_e32 v21, v102
.LBB0_48:
	v_add_u32_e32 v4, 0x300, v4
	v_mad_u64_u32 v[22:23], s[20:21], v20, s3, v[2:3]
	s_and_b64 vcc, exec, s[0:1]
	v_ashrrev_i32_e32 v4, 6, v4
	s_waitcnt vmcnt(0)
	ds_write_b32 v22, v21
	s_cbranch_vccnz .LBB0_41
	v_add_u32_e32 v20, s17, v4
	v_ashrrev_i32_e32 v21, 31, v20
	v_lshlrev_b64 v[20:21], 12, v[20:21]
	v_lshl_add_u64 v[20:21], v[12:13], 0, v[20:21]
	v_mov_b32_e32 v19, v103
	v_mov_b32_e32 v100, v104
	v_mov_b32_e32 v101, v105
	v_mov_b32_e32 v102, v106
	v_mov_b32_e32 v103, v107
	v_mov_b32_e32 v104, v108
	v_mov_b32_e32 v105, v109
	v_mov_b32_e32 v106, v110
	v_mov_b32_e32 v107, v111
	v_mov_b32_e32 v108, v112
	v_mov_b32_e32 v109, v113
	v_mov_b32_e32 v110, v114
	v_mov_b32_e32 v111, v115
	s_branch .LBB0_41

;     ...
;     for (int i = 0; i < 16; ++i) {
;       int e = tid + 256 * i, r = e >> 6, c = e & 63;
;       int n = nt * 64 + c;
;       int sc = remap ? colmap_in(n) : n;
;       float v = sc >= 0 ? src[(size_t)(kt * 64 + r) * Nsrc + sc] : 0.f;
.LBB0_94:
	v_add_u32_e32 v4, s20, v1
	v_ashrrev_i32_e32 v20, 6, v4
	v_mov_b32_e32 v19, 0
	s_and_b64 vcc, exec, s[0:1]
	v_mov_b32_e32 v21, 0
	s_cbranch_vccnz .LBB0_96
	v_add_u32_e32 v22, s19, v20
	v_ashrrev_i32_e32 v23, 31, v22
	v_lshlrev_b64 v[22:23], 14, v[22:23]
	v_lshl_add_u64 v[22:23], v[12:13], 0, v[22:23]
	s_and_b32 s32, s20, 0xfff
	s_cbranch_scc1 .Ltc_skip10
	s_mov_b64 s[100:101], 0x10000
	v_mov_b64_e32 v[116:117], v[22:23]
	global_load_dword v100, v[116:117], off
	v_lshl_add_u64 v[116:117], v[116:117], 0, s[100:101]
	global_load_dword v101, v[116:117], off
	v_lshl_add_u64 v[116:117], v[116:117], 0, s[100:101]
	global_load_dword v102, v[116:117], off
	v_lshl_add_u64 v[116:117], v[116:117], 0, s[100:101]
	global_load_dword v103, v[116:117], off
	v_lshl_add_u64 v[116:117], v[116:117], 0, s[100:101]
	global_load_dword v104, v[116:117], off
	v_lshl_add_u64 v[116:117], v[116:117], 0, s[100:101]
	global_load_dword v105, v[116:117], off
	v_lshl_add_u64 v[116:117], v[116:117], 0, s[100:101]
	global_load_dword v106, v[116:117], off
	v_lshl_add_u64 v[116:117], v[116:117], 0, s[100:101]
	global_load_dword v107, v[116:117], off
	v_lshl_add_u64 v[116:117], v[116:117], 0, s[100:101]
	global_load_dword v108, v[116:117], off
	v_lshl_add_u64 v[116:117], v[116:117], 0, s[100:101]
	global_load_dword v109, v[116:117], off
	v_lshl_add_u64 v[116:117], v[116:117], 0, s[100:101]
	global_load_dword v110, v[116:117], off
	v_lshl_add_u64 v[116:117], v[116:117], 0, s[100:101]
	global_load_dword v111, v[116:117], off
	v_lshl_add_u64 v[116:117], v[116:117], 0, s[100:101]
	global_load_dword v112, v[116:117], off
	v_lshl_add_u64 v[116:117], v[116:117], 0, s[100:101]
	global_load_dword v113, v[116:117], off
	v_lshl_add_u64 v[116:117], v[116:117], 0, s[100:101]
	global_load_dword v114, v[116:117], off
	v_lshl_add_u64 v[116:117], v[116:117], 0, s[100:101]
	global_load_dword v115, v[116:117], off
	s_waitcnt vmcnt(0)

;     ...
;     for (int i = 0; i < 16; ++i) {
;       int e = tid + 256 * i, r = e >> 6, c = e & 63;
;       int n = nt * 64 + c;
;       int sc = remap ? colmap_in(n) : n;
;       float v = sc >= 0 ? src[(size_t)(kt * 64 + r) * Nsrc + sc] : 0.f;
;       tile[r * 65 + c] = v;
;     }
.LBB0_96:
	v_mad_u64_u32 v[22:23], s[22:23], v20, s3, v[2:3]
	v_add_u32_e32 v20, 0x100, v4
	s_and_b64 vcc, exec, s[0:1]
	v_ashrrev_i32_e32 v20, 6, v20
	s_waitcnt vmcnt(0)
	ds_write_b32 v22, v21
	s_cbranch_vccnz .LBB0_98
	v_add_u32_e32 v22, s19, v20
	v_ashrrev_i32_e32 v23, 31, v22
	v_lshlrev_b64 v[22:23], 14, v[22:23]
	v_lshl_add_u64 v[22:23], v[12:13], 0, v[22:23]
	v_mov_b32_e32 v19, v101
.LBB0_98:
	v_mad_u64_u32 v[20:21], s[22:23], v20, s3, v[2:3]
	s_waitcnt vmcnt(0)
	ds_write_b32 v20, v19
	v_add_u32_e32 v19, 0x200, v4
	v_ashrrev_i32_e32 v20, 6, v19
	v_mov_b32_e32 v19, 0
	s_and_b64 vcc, exec, s[0:1]
	v_mov_b32_e32 v21, 0
	s_cbranch_vccnz .LBB0_100
	v_add_u32_e32 v22, s19, v20
	v_ashrrev_i32_e32 v23, 31, v22
	v_lshlrev_b64 v[22:23], 14, v[22:23]
	v_lshl_add_u64 v[22:23], v[12:13], 0, v[22:23]
	v_mov_b32_e32 v21, v102
.LBB0_100:
	v_add_u32_e32 v4, 0x300, v4
	v_mad_u64_u32 v[22:23], s[22:23], v20, s3, v[2:3]
	s_and_b64 vcc, exec, s[0:1]
	v_ashrrev_i32_e32 v4, 6, v4
	s_waitcnt vmcnt(0)
	ds_write_b32 v22, v21
	s_cbranch_vccnz .LBB0_93
	v_add_u32_e32 v20, s19, v4
	v_ashrrev_i32_e32 v21, 31, v20
	v_lshlrev_b64 v[20:21], 14, v[20:21]
	v_lshl_add_u64 v[20:21], v[12:13], 0, v[20:21]
	v_mov_b32_e32 v19, v103
	v_mov_b32_e32 v100, v104
	v_mov_b32_e32 v101, v105
	v_mov_b32_e32 v102, v106
	v_mov_b32_e32 v103, v107
	v_mov_b32_e32 v104, v108
	v_mov_b32_e32 v105, v109
	v_mov_b32_e32 v106, v110
	v_mov_b32_e32 v107, v111
	v_mov_b32_e32 v108, v112
	v_mov_b32_e32 v109, v113
	v_mov_b32_e32 v110, v114
	v_mov_b32_e32 v111, v115
	s_branch .LBB0_93

;     ...
;     for (int i = 0; i < 16; ++i) {
;       int e = tid + 256 * i, r = e >> 6, c = e & 63;
;       int n = nt * 64 + c;
;       int sc = remap ? colmap_in(n) : n;
;       float v = sc >= 0 ? src[(size_t)(kt * 64 + r) * Nsrc + sc] : 0.f;
.LBB0_107:
	v_add_u32_e32 v4, s14, v1
	v_ashrrev_i32_e32 v20, 6, v4
	v_mov_b32_e32 v19, 0
	s_and_b64 vcc, exec, s[0:1]
	v_mov_b32_e32 v21, 0
	s_cbranch_vccnz .LBB0_109
	v_add_u32_e32 v22, s13, v20
	v_ashrrev_i32_e32 v23, 31, v22
	v_lshlrev_b64 v[22:23], 12, v[22:23]
	v_lshl_add_u64 v[22:23], v[12:13], 0, v[22:23]
	s_and_b32 s32, s14, 0xfff
	s_cbranch_scc1 .Ltc_skip9
	s_mov_b64 s[100:101], 0x4000
	v_mov_b64_e32 v[116:117], v[22:23]
	global_load_dword v100, v[116:117], off
	v_lshl_add_u64 v[116:117], v[116:117], 0, s[100:101]
	global_load_dword v101, v[116:117], off
	v_lshl_add_u64 v[116:117], v[116:117], 0, s[100:101]
	global_load_dword v102, v[116:117], off
	v_lshl_add_u64 v[116:117], v[116:117], 0, s[100:101]
	global_load_dword v103, v[116:117], off
	v_lshl_add_u64 v[116:117], v[116:117], 0, s[100:101]
	global_load_dword v104, v[116:117], off
	v_lshl_add_u64 v[116:117], v[116:117], 0, s[100:101]
	global_load_dword v105, v[116:117], off
	v_lshl_add_u64 v[116:117], v[116:117], 0, s[100:101]
	global_load_dword v106, v[116:117], off
	v_lshl_add_u64 v[116:117], v[116:117], 0, s[100:101]
	global_load_dword v107, v[116:117], off
	v_lshl_add_u64 v[116:117], v[116:117], 0, s[100:101]
	global_load_dword v108, v[116:117], off
	v_lshl_add_u64 v[116:117], v[116:117], 0, s[100:101]
	global_load_dword v109, v[116:117], off
	v_lshl_add_u64 v[116:117], v[116:117], 0, s[100:101]
	global_load_dword v110, v[116:117], off
	v_lshl_add_u64 v[116:117], v[116:117], 0, s[100:101]
	global_load_dword v111, v[116:117], off
	v_lshl_add_u64 v[116:117], v[116:117], 0, s[100:101]
	global_load_dword v112, v[116:117], off
	v_lshl_add_u64 v[116:117], v[116:117], 0, s[100:101]
	global_load_dword v113, v[116:117], off
	v_lshl_add_u64 v[116:117], v[116:117], 0, s[100:101]
	global_load_dword v114, v[116:117], off
	v_lshl_add_u64 v[116:117], v[116:117], 0, s[100:101]
	global_load_dword v115, v[116:117], off
	s_waitcnt vmcnt(0)

;     ...
;     for (int i = 0; i < 16; ++i) {
;       int e = tid + 256 * i, r = e >> 6, c = e & 63;
;       int n = nt * 64 + c;
;       int sc = remap ? colmap_in(n) : n;
;       float v = sc >= 0 ? src[(size_t)(kt * 64 + r) * Nsrc + sc] : 0.f;
;       tile[r * 65 + c] = v;
;     }
.LBB0_109:
	v_mad_u64_u32 v[22:23], s[16:17], v20, s3, v[2:3]
	v_add_u32_e32 v20, 0x100, v4
	s_and_b64 vcc, exec, s[0:1]
	v_ashrrev_i32_e32 v20, 6, v20
	s_waitcnt vmcnt(0)
	ds_write_b32 v22, v21
	s_cbranch_vccnz .LBB0_111
	v_add_u32_e32 v22, s13, v20
	v_ashrrev_i32_e32 v23, 31, v22
	v_lshlrev_b64 v[22:23], 12, v[22:23]
	v_lshl_add_u64 v[22:23], v[12:13], 0, v[22:23]
	v_mov_b32_e32 v19, v101
.LBB0_111:
	v_mad_u64_u32 v[20:21], s[16:17], v20, s3, v[2:3]
	s_waitcnt vmcnt(0)
	ds_write_b32 v20, v19
	v_add_u32_e32 v19, 0x200, v4
	v_ashrrev_i32_e32 v20, 6, v19
	v_mov_b32_e32 v19, 0
	s_and_b64 vcc, exec, s[0:1]
	v_mov_b32_e32 v21, 0
	s_cbranch_vccnz .LBB0_113
	v_add_u32_e32 v22, s13, v20
	v_ashrrev_i32_e32 v23, 31, v22
	v_lshlrev_b64 v[22:23], 12, v[22:23]
	v_lshl_add_u64 v[22:23], v[12:13], 0, v[22:23]
	v_mov_b32_e32 v21, v102
.LBB0_113:
	v_add_u32_e32 v4, 0x300, v4
	v_mad_u64_u32 v[22:23], s[16:17], v20, s3, v[2:3]
	s_and_b64 vcc, exec, s[0:1]
	v_ashrrev_i32_e32 v4, 6, v4
	s_waitcnt vmcnt(0)
	ds_write_b32 v22, v21
	s_cbranch_vccnz .LBB0_106
	v_add_u32_e32 v20, s13, v4
	v_ashrrev_i32_e32 v21, 31, v20
	v_lshlrev_b64 v[20:21], 12, v[20:21]
	v_lshl_add_u64 v[20:21], v[12:13], 0, v[20:21]
	v_mov_b32_e32 v19, v103
	v_mov_b32_e32 v100, v104
	v_mov_b32_e32 v101, v105
	v_mov_b32_e32 v102, v106
	v_mov_b32_e32 v103, v107
	v_mov_b32_e32 v104, v108
	v_mov_b32_e32 v105, v109
	v_mov_b32_e32 v106, v110
	v_mov_b32_e32 v107, v111
	v_mov_b32_e32 v108, v112
	v_mov_b32_e32 v109, v113
	v_mov_b32_e32 v110, v114
	v_mov_b32_e32 v111, v115
	s_branch .LBB0_106

; DI int crow(int i, int h) { return (i & 3) + 8 * (i >> 2) + 4 * h; }
; DI void stage_bias(float* tab, const float* rel, int col) {
;   for (int d = threadIdx.x; d < 132; d += NTHREADS) tab[d] = rel[BUCKET_LUT[d < 128 ? d : 128] * 16 + col] * LOG2E;
; }
; DI void diff_item(const Params& P0_, int l, int b, int item, uchar* smem) {
;     ...
;       qk_tile(st, qf, 0, 2, Ks, r31, h);
;       if (far) {
;         softmax_far<2>(st, c2, bfar, m0, l0, O0, pf);
;       } else {
; #pragma unroll
;         for (int kt = 0; kt < 2; ++kt)
; #pragma unroll
;           for (int i = 0; i < 16; ++i) { int dist = qpos - (k0 + 32 * kt + crow(i, h)); st[kt][i] = dist >= 0 ? st[kt][i] * c2 + bias_at(tab, dist) : -INFINITY; }
.LBB0_1023:
	v_cmp_le_i32_e32 vcc, s21, v174
	s_and_saveexec_b64 s[12:13], vcc
	s_cbranch_execz .LBB0_1020
	v_add_u32_e32 v186, v0, v160
	ds_read_b32 v184, v1 offset:18944
	ds_read_b128 v[66:69], v186
	ds_read_b128 v[70:73], v186 offset:32
	s_movk_i32 s14, 0x80
	v_add_u32_e32 v183, v176, v175
	s_waitcnt lgkmcnt(1)
	v_mfma_f32_32x32x16_bf16 v[82:97], v[66:69], v[106:109], 0
	ds_read_b128 v[66:69], v186 offset:4608
	ds_read_b128 v[130:133], v186 offset:4640
	v_cmp_gt_i32_e64 s[48:49], s14, v175
	v_add_u32_e32 v185, 63, v183
	s_waitcnt lgkmcnt(2)
	v_mfma_f32_32x32x16_bf16 v[82:97], v[70:73], v[98:101], v[82:97]
	s_waitcnt lgkmcnt(1)
	v_mfma_f32_32x32x16_bf16 v[66:81], v[66:69], v[106:109], 0
	s_waitcnt lgkmcnt(0)
	v_mfma_f32_32x32x16_bf16 v[66:81], v[130:133], v[98:101], v[66:81]
	s_and_saveexec_b64 s[14:15], s[48:49]
	s_xor_b64 s[14:15], exec, s[14:15]
	s_cbranch_execz .LBB0_1092
	s_mov_b32 s32, 0x3e8293ee
	s_movk_i32 s100, 0x81
	v_mov_b32_e32 v206, 0xff800000
	v_mov_b32_e32 v207, 0x47fc
	ds_write_b32 v207, v206
	v_add_u32_e32 v204, 1, v185
	v_med3_i32 v204, v204, 0, s100
	v_lshlrev_b32_e32 v204, 2, v204
	ds_read_b32 v188, v204 offset:18428
	v_add_u32_e32 v205, 63, v183
	v_med3_i32 v205, v205, 0, s100
	v_lshlrev_b32_e32 v205, 2, v205
	ds_read_b32 v189, v205 offset:18428
	v_add_u32_e32 v204, 62, v183
	v_med3_i32 v204, v204, 0, s100
	v_lshlrev_b32_e32 v204, 2, v204
	ds_read_b32 v190, v204 offset:18428
	v_add_u32_e32 v205, 61, v183
	v_med3_i32 v205, v205, 0, s100
	v_lshlrev_b32_e32 v205, 2, v205
	ds_read_b32 v191, v205 offset:18428
	v_add_u32_e32 v204, 56, v183
	v_med3_i32 v204, v204, 0, s100
	v_lshlrev_b32_e32 v204, 2, v204
	ds_read_b32 v192, v204 offset:18428
	v_add_u32_e32 v205, 55, v183
	v_med3_i32 v205, v205, 0, s100
	v_lshlrev_b32_e32 v205, 2, v205
	ds_read_b32 v193, v205 offset:18428
	v_add_u32_e32 v204, 54, v183
	v_med3_i32 v204, v204, 0, s100
	v_lshlrev_b32_e32 v204, 2, v204
	ds_read_b32 v194, v204 offset:18428
	v_add_u32_e32 v205, 53, v183
	v_med3_i32 v205, v205, 0, s100
	v_lshlrev_b32_e32 v205, 2, v205
	ds_read_b32 v195, v205 offset:18428
	v_add_u32_e32 v204, 48, v183
	v_med3_i32 v204, v204, 0, s100
	v_lshlrev_b32_e32 v204, 2, v204
	ds_read_b32 v196, v204 offset:18428
	v_add_u32_e32 v205, 47, v183
	v_med3_i32 v205, v205, 0, s100
	v_lshlrev_b32_e32 v205, 2, v205
	ds_read_b32 v197, v205 offset:18428
	v_add_u32_e32 v204, 46, v183
	v_med3_i32 v204, v204, 0, s100
	v_lshlrev_b32_e32 v204, 2, v204
	ds_read_b32 v198, v204 offset:18428
	v_add_u32_e32 v205, 45, v183
	v_med3_i32 v205, v205, 0, s100
	v_lshlrev_b32_e32 v205, 2, v205
	ds_read_b32 v199, v205 offset:18428
	v_add_u32_e32 v204, 40, v183
	v_med3_i32 v204, v204, 0, s100
	v_lshlrev_b32_e32 v204, 2, v204
	ds_read_b32 v200, v204 offset:18428
	v_add_u32_e32 v205, 39, v183
	v_med3_i32 v205, v205, 0, s100
	v_lshlrev_b32_e32 v205, 2, v205
	ds_read_b32 v201, v205 offset:18428
	v_add_u32_e32 v204, 38, v183
	v_med3_i32 v204, v204, 0, s100
	v_lshlrev_b32_e32 v204, 2, v204
	ds_read_b32 v202, v204 offset:18428
	v_add_u32_e32 v205, 37, v183
	v_med3_i32 v205, v205, 0, s100
	v_lshlrev_b32_e32 v205, 2, v205
	ds_read_b32 v203, v205 offset:18428
	s_waitcnt lgkmcnt(0)
; DI int crow(int i, int h) { return (i & 3) + 8 * (i >> 2) + 4 * h; }
; template <int NO, bool COND = true>
; DI void softmax_step(f32x16 st[2], float& m, float& lsum, f32x16* O, bf16x8 pf[4]) {
;   float mx = fmaxf(m, fmaxf(max16(st[0]), max16(st[1])));
;   mx = fmaxf(mx, __shfl_xor(mx, 32, 64));
;   sm_rescale<NO, COND>(m, mx, lsum, O);
; DI void diff_item(const Params& P0_, int l, int b, int item, uchar* smem) {
;     ...
;         for (int kt = 0; kt < 2; ++kt)
; #pragma unroll
;           for (int i = 0; i < 16; ++i) { int dist = qpos - (k0 + 32 * kt + crow(i, h)); st[kt][i] = dist >= 0 ? st[kt][i] * c2 + bias_at(tab, dist) : -INFINITY; }
;         softmax_step<2>(st, m0, l0, O0, pf);
	v_fma_f32 v131, v82, s32, v188
	v_fma_f32 v130, v83, s32, v189
	v_fma_f32 v83, v84, s32, v190
	v_fma_f32 v82, v85, s32, v191
	v_fma_f32 v85, v86, s32, v192
	v_fma_f32 v84, v87, s32, v193
	v_fma_f32 v87, v88, s32, v194
	v_fma_f32 v86, v89, s32, v195
	v_fma_f32 v89, v90, s32, v196
	v_fma_f32 v88, v91, s32, v197
	v_fma_f32 v91, v92, s32, v198
	v_fma_f32 v90, v93, s32, v199
	v_fma_f32 v93, v94, s32, v200
	v_fma_f32 v92, v95, s32, v201
	v_fma_f32 v95, v96, s32, v202
	v_fma_f32 v94, v97, s32, v203
	v_add_u32_e32 v204, 32, v183
	v_med3_i32 v204, v204, 0, s100
	v_lshlrev_b32_e32 v204, 2, v204
	ds_read_b32 v188, v204 offset:18428
	v_add_u32_e32 v205, 31, v183
	v_med3_i32 v205, v205, 0, s100
	v_lshlrev_b32_e32 v205, 2, v205
	ds_read_b32 v189, v205 offset:18428
	v_add_u32_e32 v204, 30, v183
	v_med3_i32 v204, v204, 0, s100
	v_lshlrev_b32_e32 v204, 2, v204
	ds_read_b32 v190, v204 offset:18428
	v_add_u32_e32 v205, 29, v183
	v_med3_i32 v205, v205, 0, s100
	v_lshlrev_b32_e32 v205, 2, v205
	ds_read_b32 v191, v205 offset:18428
	v_add_u32_e32 v204, 24, v183
	v_med3_i32 v204, v204, 0, s100
	v_lshlrev_b32_e32 v204, 2, v204
	ds_read_b32 v192, v204 offset:18428
	v_add_u32_e32 v205, 23, v183
	v_med3_i32 v205, v205, 0, s100
	v_lshlrev_b32_e32 v205, 2, v205
	ds_read_b32 v193, v205 offset:18428
	v_add_u32_e32 v204, 22, v183
	v_med3_i32 v204, v204, 0, s100
	v_lshlrev_b32_e32 v204, 2, v204
	ds_read_b32 v194, v204 offset:18428
	v_add_u32_e32 v205, 21, v183
	v_med3_i32 v205, v205, 0, s100
	v_lshlrev_b32_e32 v205, 2, v205
	ds_read_b32 v195, v205 offset:18428
	v_add_u32_e32 v204, 16, v183
	v_med3_i32 v204, v204, 0, s100
	v_lshlrev_b32_e32 v204, 2, v204
	ds_read_b32 v196, v204 offset:18428
	v_add_u32_e32 v205, 15, v183
	v_med3_i32 v205, v205, 0, s100
	v_lshlrev_b32_e32 v205, 2, v205
	ds_read_b32 v197, v205 offset:18428
	v_add_u32_e32 v204, 14, v183
	v_med3_i32 v204, v204, 0, s100
	v_lshlrev_b32_e32 v204, 2, v204
	ds_read_b32 v198, v204 offset:18428
	v_add_u32_e32 v205, 13, v183
	v_med3_i32 v205, v205, 0, s100
	v_lshlrev_b32_e32 v205, 2, v205
	ds_read_b32 v199, v205 offset:18428
	v_add_u32_e32 v204, 8, v183
	v_med3_i32 v204, v204, 0, s100
	v_lshlrev_b32_e32 v204, 2, v204
	ds_read_b32 v200, v204 offset:18428
	v_add_u32_e32 v205, 7, v183
	v_med3_i32 v205, v205, 0, s100
	v_lshlrev_b32_e32 v205, 2, v205
	ds_read_b32 v201, v205 offset:18428
	v_add_u32_e32 v204, 6, v183
	v_med3_i32 v204, v204, 0, s100
	v_lshlrev_b32_e32 v204, 2, v204
	ds_read_b32 v202, v204 offset:18428
	v_add_u32_e32 v205, 5, v183
	v_med3_i32 v205, v205, 0, s100
	v_lshlrev_b32_e32 v205, 2, v205
	ds_read_b32 v203, v205 offset:18428
	s_waitcnt lgkmcnt(0)
	v_fma_f32 v97, v66, s32, v188
	v_fma_f32 v96, v67, s32, v189
	v_fma_f32 v67, v68, s32, v190
	v_fma_f32 v66, v69, s32, v191
	v_fma_f32 v69, v70, s32, v192
	v_fma_f32 v68, v71, s32, v193
	v_fma_f32 v71, v72, s32, v194
	v_fma_f32 v70, v73, s32, v195
	v_fma_f32 v73, v74, s32, v196
	v_fma_f32 v72, v75, s32, v197
	v_fma_f32 v75, v76, s32, v198
	v_fma_f32 v74, v77, s32, v199
	v_fma_f32 v77, v78, s32, v200
	v_fma_f32 v76, v79, s32, v201
	v_fma_f32 v79, v80, s32, v202
	v_fma_f32 v78, v81, s32, v203
	v_max_f32_e32 v80, v130, v130
	v_max_f32_e32 v81, v131, v131
	v_max_f32_e32 v132, v86, v86
	v_max_f32_e32 v133, v87, v87
	v_max_f32_e32 v134, v92, v92
	v_max_f32_e32 v135, v93, v93
	v_max_f32_e32 v80, v81, v80
	v_max3_f32 v81, v82, v85, v84
	v_max_f32_e32 v132, v133, v132
	v_max3_f32 v133, v88, v91, v90
	v_max_f32_e32 v134, v135, v134
	v_max3_f32 v80, v80, v83, v81
	v_max3_f32 v81, v132, v89, v133
	v_max3_f32 v132, v134, v95, v94
	v_max3_f32 v80, v80, v81, v132
	v_max_f32_e32 v81, v96, v96
	v_max_f32_e32 v132, v97, v97
	v_max_f32_e32 v133, v70, v70
	v_max_f32_e32 v134, v71, v71
	v_max_f32_e32 v135, v76, v76
	v_max_f32_e32 v136, v77, v77
	v_max_f32_e32 v81, v132, v81
	v_max3_f32 v132, v66, v69, v68
	v_max_f32_e32 v133, v134, v133
	v_max3_f32 v134, v72, v75, v74
	v_max_f32_e32 v135, v136, v135
	v_max3_f32 v81, v81, v67, v132
	v_max3_f32 v132, v133, v73, v134
	v_max3_f32 v133, v135, v79, v78
	v_max3_f32 v81, v81, v132, v133
	v_max3_f32 v80, v187, v80, v81
	ds_bpermute_b32 v81, v139, v80
	s_waitcnt lgkmcnt(0)
	v_max_f32_e32 v81, v81, v81
	v_max_f32_e32 v182, v80, v81
	v_cmp_gt_f32_e32 vcc, v182, v187
	s_cbranch_vccz .LBB0_1091
	v_sub_f32_e32 v80, v187, v182
	v_exp_f32_e32 v80, v80
	s_nop 0
	v_mul_f32_e32 v180, v180, v80
	v_pk_mul_f32 v[16:17], v[16:17], v[80:81] op_sel_hi:[1,0]
	v_pk_mul_f32 v[14:15], v[14:15], v[80:81] op_sel_hi:[1,0]
	v_pk_mul_f32 v[12:13], v[12:13], v[80:81] op_sel_hi:[1,0]
	v_pk_mul_f32 v[10:11], v[10:11], v[80:81] op_sel_hi:[1,0]
	v_pk_mul_f32 v[8:9], v[8:9], v[80:81] op_sel_hi:[1,0]
	v_pk_mul_f32 v[6:7], v[6:7], v[80:81] op_sel_hi:[1,0]
	v_pk_mul_f32 v[4:5], v[4:5], v[80:81] op_sel_hi:[1,0]
	v_pk_mul_f32 v[2:3], v[2:3], v[80:81] op_sel_hi:[1,0]
	v_pk_mul_f32 v[48:49], v[48:49], v[80:81] op_sel_hi:[1,0]
	v_pk_mul_f32 v[46:47], v[46:47], v[80:81] op_sel_hi:[1,0]
	v_pk_mul_f32 v[44:45], v[44:45], v[80:81] op_sel_hi:[1,0]
	v_pk_mul_f32 v[42:43], v[42:43], v[80:81] op_sel_hi:[1,0]
	v_pk_mul_f32 v[40:41], v[40:41], v[80:81] op_sel_hi:[1,0]
	v_pk_mul_f32 v[38:39], v[38:39], v[80:81] op_sel_hi:[1,0]
	v_pk_mul_f32 v[36:37], v[36:37], v[80:81] op_sel_hi:[1,0]
	v_pk_mul_f32 v[34:35], v[34:35], v[80:81] op_sel_hi:[1,0]

; DI f32x16 mfma32(bf16x8 a, bf16x8 b, f32x16 c) { return __builtin_amdgcn_mfma_f32_32x32x16_bf16(a, b, c, 0, 0, 0); }
; DI int crow(int i, int h) { return (i & 3) + 8 * (i >> 2) + 4 * h; }
; DI void pv_tile(f32x16 O[2], const bf16x8 pf[4], const uchar* Vs, int lane) {
;   const int h = lane >> 5, blk = (lane >> 4) & 1, q4 = (lane & 15) >> 2, p = lane & 3;
; #pragma unroll
;   for (int sp = 0; sp < 4; ++sp) {
; #pragma unroll
;     for (int dt = 0; dt < 2; ++dt) {
;       const uchar* a = Vs + (16 * sp + 4 * h + q4) * 144 + 64 * dt + 32 * blk + 8 * p;
;       s16x4 lo = tr_read(a), hi = tr_read(a + 8 * 144);
;       bf16x8 vf = __builtin_shufflevector(lo, hi, 0, 1, 2, 3, 4, 5, 6, 7);
;       O[dt] = mfma32(vf, pf[sp], O[dt]);
;     }
;   }
; }
; DI void diff_item(const Params& P0_, int l, int b, int item, uchar* smem) {
;     ...
;       pv_tile(O0, pf, Vs, lane);
;       qk_tile(st, qf, 2, 2, Ks, r31, h);
;       if (far) {
;         softmax_far<2>(st, c2, bfar, m1, l1, O1, pf);
;       } else {
; #pragma unroll
;         for (int kt = 0; kt < 2; ++kt)
; #pragma unroll
;           for (int i = 0; i < 16; ++i) { int dist = qpos - (k0 + 32 * kt + crow(i, h)); st[kt][i] = dist >= 0 ? st[kt][i] * c2 + bias_at(tab, dist) : -INFINITY; }
.LBB0_1096:
	s_or_b64 exec, exec, s[14:15]
	s_nop 5
	ds_read_b64_tr_b16 v[74:75], v179 offset:9216
	ds_read_b64_tr_b16 v[76:77], v179 offset:10368
	v_cvt_pk_bf16_f32 v66, v142, v143
	v_cvt_pk_bf16_f32 v67, v144, v145
	v_cvt_pk_bf16_f32 v68, v146, v147
	v_cvt_pk_bf16_f32 v69, v148, v149
	s_waitcnt lgkmcnt(0)
	v_mfma_f32_32x32x16_bf16 v[2:17], v[74:77], v[134:137], v[2:17]
	ds_read_b64_tr_b16 v[74:75], v179 offset:9280
	ds_read_b64_tr_b16 v[76:77], v179 offset:10432
	v_cvt_pk_bf16_f32 v70, v150, v151
	v_cvt_pk_bf16_f32 v71, v152, v153
	v_cvt_pk_bf16_f32 v72, v154, v155
	v_cvt_pk_bf16_f32 v73, v156, v157
	s_waitcnt lgkmcnt(0)
	v_mfma_f32_32x32x16_bf16 v[34:49], v[74:77], v[134:137], v[34:49]
	ds_read_b64_tr_b16 v[74:75], v179 offset:11520
	ds_read_b64_tr_b16 v[76:77], v179 offset:12672
	s_waitcnt lgkmcnt(0)
	v_mfma_f32_32x32x16_bf16 v[2:17], v[74:77], v[130:133], v[2:17]
	ds_read_b64_tr_b16 v[74:75], v179 offset:11584
	ds_read_b64_tr_b16 v[76:77], v179 offset:12736
	s_waitcnt lgkmcnt(0)
	v_mfma_f32_32x32x16_bf16 v[34:49], v[74:77], v[130:133], v[34:49]
	ds_read_b64_tr_b16 v[74:75], v179 offset:13824
	ds_read_b64_tr_b16 v[76:77], v179 offset:14976
	s_waitcnt lgkmcnt(0)
	v_mfma_f32_32x32x16_bf16 v[2:17], v[74:77], v[66:69], v[2:17]
	ds_read_b64_tr_b16 v[74:75], v179 offset:13888
	ds_read_b64_tr_b16 v[76:77], v179 offset:15040
	s_waitcnt lgkmcnt(0)
	v_mfma_f32_32x32x16_bf16 v[34:49], v[74:77], v[66:69], v[34:49]
	ds_read_b64_tr_b16 v[66:67], v179 offset:16128
	ds_read_b64_tr_b16 v[68:69], v179 offset:17280
	s_waitcnt lgkmcnt(0)
	v_mfma_f32_32x32x16_bf16 v[2:17], v[66:69], v[70:73], v[2:17]
	ds_read_b64_tr_b16 v[66:67], v179 offset:16192
	ds_read_b64_tr_b16 v[68:69], v179 offset:17344
	s_waitcnt lgkmcnt(0)
	v_mfma_f32_32x32x16_bf16 v[34:49], v[66:69], v[70:73], v[34:49]
	ds_read_b128 v[66:69], v186 offset:64
	ds_read_b128 v[70:73], v186 offset:96
	ds_read_b128 v[130:133], v186 offset:4704
	s_waitcnt lgkmcnt(2)
	v_mfma_f32_32x32x16_bf16 v[82:97], v[66:69], v[102:105], 0
	ds_read_b128 v[66:69], v186 offset:4672
	s_waitcnt lgkmcnt(2)
	v_mfma_f32_32x32x16_bf16 v[82:97], v[70:73], v[110:113], v[82:97]
	s_waitcnt lgkmcnt(0)
	v_mfma_f32_32x32x16_bf16 v[66:81], v[66:69], v[102:105], 0
	v_mfma_f32_32x32x16_bf16 v[66:81], v[130:133], v[110:113], v[66:81]
	s_and_saveexec_b64 s[14:15], s[48:49]
	s_xor_b64 s[14:15], exec, s[14:15]
	s_cbranch_execz .LBB0_1164
	s_mov_b32 s32, 0x3e8293ee
	s_movk_i32 s100, 0x81
	v_mov_b32_e32 v206, 0xff800000
	v_mov_b32_e32 v207, 0x47fc
	ds_write_b32 v207, v206
	v_add_u32_e32 v204, 1, v185
	v_med3_i32 v204, v204, 0, s100
	v_lshlrev_b32_e32 v204, 2, v204
	ds_read_b32 v188, v204 offset:18428
	v_add_u32_e32 v205, 63, v183
	v_med3_i32 v205, v205, 0, s100
	v_lshlrev_b32_e32 v205, 2, v205
	ds_read_b32 v189, v205 offset:18428
	v_add_u32_e32 v204, 62, v183
	v_med3_i32 v204, v204, 0, s100
	v_lshlrev_b32_e32 v204, 2, v204
	ds_read_b32 v190, v204 offset:18428
	v_add_u32_e32 v205, 61, v183
	v_med3_i32 v205, v205, 0, s100
	v_lshlrev_b32_e32 v205, 2, v205
	ds_read_b32 v191, v205 offset:18428
	v_add_u32_e32 v204, 56, v183
	v_med3_i32 v204, v204, 0, s100
	v_lshlrev_b32_e32 v204, 2, v204
	ds_read_b32 v192, v204 offset:18428
	v_add_u32_e32 v205, 55, v183
	v_med3_i32 v205, v205, 0, s100
	v_lshlrev_b32_e32 v205, 2, v205
	ds_read_b32 v193, v205 offset:18428
	v_add_u32_e32 v204, 54, v183
	v_med3_i32 v204, v204, 0, s100
	v_lshlrev_b32_e32 v204, 2, v204
	ds_read_b32 v194, v204 offset:18428
	v_add_u32_e32 v205, 53, v183
	v_med3_i32 v205, v205, 0, s100
	v_lshlrev_b32_e32 v205, 2, v205
	ds_read_b32 v195, v205 offset:18428
	v_add_u32_e32 v204, 48, v183
	v_med3_i32 v204, v204, 0, s100
	v_lshlrev_b32_e32 v204, 2, v204
	ds_read_b32 v196, v204 offset:18428
	v_add_u32_e32 v205, 47, v183
	v_med3_i32 v205, v205, 0, s100
	v_lshlrev_b32_e32 v205, 2, v205
	ds_read_b32 v197, v205 offset:18428
	v_add_u32_e32 v204, 46, v183
	v_med3_i32 v204, v204, 0, s100
	v_lshlrev_b32_e32 v204, 2, v204
	ds_read_b32 v198, v204 offset:18428
	v_add_u32_e32 v205, 45, v183
	v_med3_i32 v205, v205, 0, s100
	v_lshlrev_b32_e32 v205, 2, v205
	ds_read_b32 v199, v205 offset:18428
	v_add_u32_e32 v204, 40, v183
	v_med3_i32 v204, v204, 0, s100
	v_lshlrev_b32_e32 v204, 2, v204
	ds_read_b32 v200, v204 offset:18428
	v_add_u32_e32 v205, 39, v183
	v_med3_i32 v205, v205, 0, s100
	v_lshlrev_b32_e32 v205, 2, v205
	ds_read_b32 v201, v205 offset:18428
	v_add_u32_e32 v204, 38, v183
	v_med3_i32 v204, v204, 0, s100
	v_lshlrev_b32_e32 v204, 2, v204
	ds_read_b32 v202, v204 offset:18428
	v_add_u32_e32 v205, 37, v183
	v_med3_i32 v205, v205, 0, s100
	v_lshlrev_b32_e32 v205, 2, v205
	ds_read_b32 v203, v205 offset:18428
	s_waitcnt lgkmcnt(0)
; DI int crow(int i, int h) { return (i & 3) + 8 * (i >> 2) + 4 * h; }
; template <int NO, bool COND = true>
; DI void softmax_step(f32x16 st[2], float& m, float& lsum, f32x16* O, bf16x8 pf[4]) {
;   float mx = fmaxf(m, fmaxf(max16(st[0]), max16(st[1])));
;   mx = fmaxf(mx, __shfl_xor(mx, 32, 64));
;   sm_rescale<NO, COND>(m, mx, lsum, O);
; DI void diff_item(const Params& P0_, int l, int b, int item, uchar* smem) {
;     ...
;         for (int kt = 0; kt < 2; ++kt)
; #pragma unroll
;           for (int i = 0; i < 16; ++i) { int dist = qpos - (k0 + 32 * kt + crow(i, h)); st[kt][i] = dist >= 0 ? st[kt][i] * c2 + bias_at(tab, dist) : -INFINITY; }
;         softmax_step<2>(st, m1, l1, O1, pf);
	v_fma_f32 v131, v82, s32, v188
	v_fma_f32 v130, v83, s32, v189
	v_fma_f32 v83, v84, s32, v190
	v_fma_f32 v82, v85, s32, v191
	v_fma_f32 v85, v86, s32, v192
	v_fma_f32 v84, v87, s32, v193
	v_fma_f32 v87, v88, s32, v194
	v_fma_f32 v86, v89, s32, v195
	v_fma_f32 v89, v90, s32, v196
	v_fma_f32 v88, v91, s32, v197
	v_fma_f32 v91, v92, s32, v198
	v_fma_f32 v90, v93, s32, v199
	v_fma_f32 v93, v94, s32, v200
	v_fma_f32 v92, v95, s32, v201
	v_fma_f32 v95, v96, s32, v202
	v_fma_f32 v94, v97, s32, v203
	v_add_u32_e32 v204, 32, v183
	v_med3_i32 v204, v204, 0, s100
	v_lshlrev_b32_e32 v204, 2, v204
	ds_read_b32 v188, v204 offset:18428
	v_add_u32_e32 v205, 31, v183
	v_med3_i32 v205, v205, 0, s100
	v_lshlrev_b32_e32 v205, 2, v205
	ds_read_b32 v189, v205 offset:18428
	v_add_u32_e32 v204, 30, v183
	v_med3_i32 v204, v204, 0, s100
	v_lshlrev_b32_e32 v204, 2, v204
	ds_read_b32 v190, v204 offset:18428
	v_add_u32_e32 v205, 29, v183
	v_med3_i32 v205, v205, 0, s100
	v_lshlrev_b32_e32 v205, 2, v205
	ds_read_b32 v191, v205 offset:18428
	v_add_u32_e32 v204, 24, v183
	v_med3_i32 v204, v204, 0, s100
	v_lshlrev_b32_e32 v204, 2, v204
	ds_read_b32 v192, v204 offset:18428
	v_add_u32_e32 v205, 23, v183
	v_med3_i32 v205, v205, 0, s100
	v_lshlrev_b32_e32 v205, 2, v205
	ds_read_b32 v193, v205 offset:18428
	v_add_u32_e32 v204, 22, v183
	v_med3_i32 v204, v204, 0, s100
	v_lshlrev_b32_e32 v204, 2, v204
	ds_read_b32 v194, v204 offset:18428
	v_add_u32_e32 v205, 21, v183
	v_med3_i32 v205, v205, 0, s100
	v_lshlrev_b32_e32 v205, 2, v205
	ds_read_b32 v195, v205 offset:18428
	v_add_u32_e32 v204, 16, v183
	v_med3_i32 v204, v204, 0, s100
	v_lshlrev_b32_e32 v204, 2, v204
	ds_read_b32 v196, v204 offset:18428
	v_add_u32_e32 v205, 15, v183
	v_med3_i32 v205, v205, 0, s100
	v_lshlrev_b32_e32 v205, 2, v205
	ds_read_b32 v197, v205 offset:18428
	v_add_u32_e32 v204, 14, v183
	v_med3_i32 v204, v204, 0, s100
	v_lshlrev_b32_e32 v204, 2, v204
	ds_read_b32 v198, v204 offset:18428
	v_add_u32_e32 v205, 13, v183
	v_med3_i32 v205, v205, 0, s100
	v_lshlrev_b32_e32 v205, 2, v205
	ds_read_b32 v199, v205 offset:18428
	v_add_u32_e32 v204, 8, v183
	v_med3_i32 v204, v204, 0, s100
	v_lshlrev_b32_e32 v204, 2, v204
	ds_read_b32 v200, v204 offset:18428
	v_add_u32_e32 v205, 7, v183
	v_med3_i32 v205, v205, 0, s100
	v_lshlrev_b32_e32 v205, 2, v205
	ds_read_b32 v201, v205 offset:18428
	v_add_u32_e32 v204, 6, v183
	v_med3_i32 v204, v204, 0, s100
	v_lshlrev_b32_e32 v204, 2, v204
	ds_read_b32 v202, v204 offset:18428
	v_add_u32_e32 v205, 5, v183
	v_med3_i32 v205, v205, 0, s100
	v_lshlrev_b32_e32 v205, 2, v205
	ds_read_b32 v203, v205 offset:18428
	s_waitcnt lgkmcnt(0)
	v_fma_f32 v97, v66, s32, v188
	v_fma_f32 v96, v67, s32, v189
	v_fma_f32 v67, v68, s32, v190
	v_fma_f32 v66, v69, s32, v191
	v_fma_f32 v69, v70, s32, v192
	v_fma_f32 v68, v71, s32, v193
	v_fma_f32 v71, v72, s32, v194
	v_fma_f32 v70, v73, s32, v195
	v_fma_f32 v73, v74, s32, v196
	v_fma_f32 v72, v75, s32, v197
	v_fma_f32 v75, v76, s32, v198
	v_fma_f32 v74, v77, s32, v199
	v_fma_f32 v77, v78, s32, v200
	v_fma_f32 v76, v79, s32, v201
	v_fma_f32 v79, v80, s32, v202
	v_fma_f32 v78, v81, s32, v203
	v_max_f32_e32 v80, v130, v130
	v_max_f32_e32 v81, v131, v131
	v_max_f32_e32 v132, v86, v86
	v_max_f32_e32 v133, v87, v87
	v_max_f32_e32 v134, v92, v92
	v_max_f32_e32 v135, v93, v93
	v_max_f32_e32 v80, v81, v80
	v_max3_f32 v81, v82, v85, v84
	v_max_f32_e32 v132, v133, v132
	v_max3_f32 v133, v88, v91, v90
	v_max_f32_e32 v134, v135, v134
	v_max3_f32 v80, v80, v83, v81
	v_max3_f32 v81, v132, v89, v133
	v_max3_f32 v132, v134, v95, v94
	v_max3_f32 v80, v80, v81, v132
	v_max_f32_e32 v81, v96, v96
	v_max_f32_e32 v132, v97, v97
	v_max_f32_e32 v133, v70, v70
	v_max_f32_e32 v134, v71, v71
	v_max_f32_e32 v135, v76, v76
	v_max_f32_e32 v136, v77, v77
	v_max_f32_e32 v81, v132, v81
	v_max3_f32 v132, v66, v69, v68
	v_max_f32_e32 v133, v134, v133
	v_max3_f32 v134, v72, v75, v74
	v_max_f32_e32 v135, v136, v135
	v_max3_f32 v81, v81, v67, v132
	v_max3_f32 v132, v133, v73, v134
	v_max3_f32 v133, v135, v79, v78
	v_max3_f32 v81, v81, v132, v133
	v_max3_f32 v80, v181, v80, v81
	ds_bpermute_b32 v81, v139, v80
	s_waitcnt lgkmcnt(0)
	v_max_f32_e32 v81, v81, v81
	v_max_f32_e32 v186, v80, v81
	v_cmp_gt_f32_e32 vcc, v186, v181
	s_cbranch_vccz .LBB0_1163
	v_sub_f32_e32 v80, v181, v186
	v_exp_f32_e32 v80, v80
	s_nop 0
	v_mul_f32_e32 v171, v171, v80
	v_pk_mul_f32 v[32:33], v[32:33], v[80:81] op_sel_hi:[1,0]
	v_pk_mul_f32 v[30:31], v[30:31], v[80:81] op_sel_hi:[1,0]
	v_pk_mul_f32 v[28:29], v[28:29], v[80:81] op_sel_hi:[1,0]
	v_pk_mul_f32 v[26:27], v[26:27], v[80:81] op_sel_hi:[1,0]
	v_pk_mul_f32 v[24:25], v[24:25], v[80:81] op_sel_hi:[1,0]
	v_pk_mul_f32 v[22:23], v[22:23], v[80:81] op_sel_hi:[1,0]
	v_pk_mul_f32 v[20:21], v[20:21], v[80:81] op_sel_hi:[1,0]
	v_pk_mul_f32 v[18:19], v[18:19], v[80:81] op_sel_hi:[1,0]
	v_pk_mul_f32 v[64:65], v[64:65], v[80:81] op_sel_hi:[1,0]
	v_pk_mul_f32 v[62:63], v[62:63], v[80:81] op_sel_hi:[1,0]
	v_pk_mul_f32 v[60:61], v[60:61], v[80:81] op_sel_hi:[1,0]
	v_pk_mul_f32 v[58:59], v[58:59], v[80:81] op_sel_hi:[1,0]
	v_pk_mul_f32 v[56:57], v[56:57], v[80:81] op_sel_hi:[1,0]
	v_pk_mul_f32 v[54:55], v[54:55], v[80:81] op_sel_hi:[1,0]
	v_pk_mul_f32 v[52:53], v[52:53], v[80:81] op_sel_hi:[1,0]
	v_pk_mul_f32 v[50:51], v[50:51], v[80:81] op_sel_hi:[1,0]

;     ...
;   for (int t = blockIdx.x; t < ntiles; t += gridDim.x) {
;     const int kt = t % nkt, nt = t / nkt;
;     __syncthreads();
; #pragma unroll 4
;     for (int i = 0; i < 16; ++i) {
;       int e = tid + 256 * i, r = e >> 6, c = e & 63;
;       int n = nt * 64 + c;
;       int sc = remap ? colmap_in(n) : n;
;       float v = sc >= 0 ? src[(size_t)(kt * 64 + r) * Nsrc + sc] : 0.f;
;       tile[r * 65 + c] = v;
;     }
.LBB0_1781:
	v_add_u32_e32 v0, s16, v3
	v_ashrrev_i32_e32 v17, 6, v0
	v_mov_b32_e32 v16, 0
	v_mov_b32_e32 v18, 0
	s_and_saveexec_b64 s[0:1], vcc
	s_cbranch_execz .LBB0_1783
	v_add_u32_e32 v18, s15, v17
	v_mad_i64_i32 v[18:19], s[18:19], v18, s20, v[10:11]
	s_and_b32 s32, s16, 0xfff
	s_cbranch_scc1 .Ltc_skip8
	s_lshl_b32 s100, s20, 2
	s_mov_b32 s101, 0
	v_mov_b64_e32 v[116:117], v[18:19]
	global_load_dword v100, v[116:117], off
	v_lshl_add_u64 v[116:117], v[116:117], 0, s[100:101]
	global_load_dword v101, v[116:117], off
	v_lshl_add_u64 v[116:117], v[116:117], 0, s[100:101]
	global_load_dword v102, v[116:117], off
	v_lshl_add_u64 v[116:117], v[116:117], 0, s[100:101]
	global_load_dword v103, v[116:117], off
	v_lshl_add_u64 v[116:117], v[116:117], 0, s[100:101]
	global_load_dword v104, v[116:117], off
	v_lshl_add_u64 v[116:117], v[116:117], 0, s[100:101]
	global_load_dword v105, v[116:117], off
	v_lshl_add_u64 v[116:117], v[116:117], 0, s[100:101]
	global_load_dword v106, v[116:117], off
	v_lshl_add_u64 v[116:117], v[116:117], 0, s[100:101]
	global_load_dword v107, v[116:117], off
	v_lshl_add_u64 v[116:117], v[116:117], 0, s[100:101]
	global_load_dword v108, v[116:117], off
	v_lshl_add_u64 v[116:117], v[116:117], 0, s[100:101]
	global_load_dword v109, v[116:117], off
	v_lshl_add_u64 v[116:117], v[116:117], 0, s[100:101]
	global_load_dword v110, v[116:117], off
	v_lshl_add_u64 v[116:117], v[116:117], 0, s[100:101]
	global_load_dword v111, v[116:117], off
	v_lshl_add_u64 v[116:117], v[116:117], 0, s[100:101]
	global_load_dword v112, v[116:117], off
	v_lshl_add_u64 v[116:117], v[116:117], 0, s[100:101]
	global_load_dword v113, v[116:117], off
	v_lshl_add_u64 v[116:117], v[116:117], 0, s[100:101]
	global_load_dword v114, v[116:117], off
	v_lshl_add_u64 v[116:117], v[116:117], 0, s[100:101]
	global_load_dword v115, v[116:117], off
	s_waitcnt vmcnt(0)
.Ltc_skip8:
	v_mov_b32_e32 v18, v100
.LBB0_1783:
	s_or_b64 exec, exec, s[0:1]
	v_mad_u64_u32 v[20:21], s[0:1], v17, s36, v[2:3]
	v_add_u32_e32 v17, 0x100, v0
	v_ashrrev_i32_e32 v17, 6, v17
	s_waitcnt vmcnt(0)
	ds_write_b32 v20, v18
	s_and_saveexec_b64 s[0:1], vcc
	s_cbranch_execz .LBB0_1785
	v_add_u32_e32 v16, s15, v17
	v_mad_i64_i32 v[18:19], s[18:19], v16, s20, v[10:11]
	v_mov_b32_e32 v16, v101
.LBB0_1785:
	s_or_b64 exec, exec, s[0:1]
	v_mad_u64_u32 v[18:19], s[0:1], v17, s36, v[2:3]
	s_waitcnt vmcnt(0)
	ds_write_b32 v18, v16
	v_add_u32_e32 v16, 0x200, v0
	v_ashrrev_i32_e32 v17, 6, v16
	v_mov_b32_e32 v16, 0
	v_mov_b32_e32 v18, 0
	s_and_saveexec_b64 s[0:1], vcc
	s_cbranch_execz .LBB0_1787
	v_add_u32_e32 v18, s15, v17
	v_mad_i64_i32 v[18:19], s[18:19], v18, s20, v[10:11]
	v_mov_b32_e32 v18, v102
.LBB0_1787:
	s_or_b64 exec, exec, s[0:1]
	v_add_u32_e32 v0, 0x300, v0
	v_mad_u64_u32 v[20:21], s[0:1], v17, s36, v[2:3]
	v_ashrrev_i32_e32 v0, 6, v0
	s_waitcnt vmcnt(0)
	ds_write_b32 v20, v18
	s_and_saveexec_b64 s[0:1], vcc
	s_cbranch_execz .LBB0_1780
	v_add_u32_e32 v16, s15, v0
	v_mad_i64_i32 v[16:17], s[18:19], v16, s20, v[10:11]
	v_mov_b32_e32 v16, v103
	v_mov_b32_e32 v100, v104
	v_mov_b32_e32 v101, v105
	v_mov_b32_e32 v102, v106
	v_mov_b32_e32 v103, v107
	v_mov_b32_e32 v104, v108
	v_mov_b32_e32 v105, v109
	v_mov_b32_e32 v106, v110
	v_mov_b32_e32 v107, v111
	v_mov_b32_e32 v108, v112
	v_mov_b32_e32 v109, v113
	v_mov_b32_e32 v110, v114
	v_mov_b32_e32 v111, v115
	s_branch .LBB0_1780

;     ...
;     for (int i = 0; i < 16; ++i) {
;       int e = tid + 256 * i, r = e >> 6, c = e & 63;
;       int n = nt * 64 + c;
;       int sc = remap ? colmap_in(n) : n;
;       float v = sc >= 0 ? src[(size_t)(kt * 64 + r) * Nsrc + sc] : 0.f;
.LBB0_1794:
	v_add_u32_e32 v0, s20, v3
	v_cndmask_b32_e64 v18, 0, 1, s[16:17]
	v_ashrrev_i32_e32 v17, 6, v0
	v_mov_b32_e32 v16, 0
	v_cmp_ne_u32_e64 s[0:1], 1, v18
	s_andn2_b64 vcc, exec, s[16:17]
	v_mov_b32_e32 v18, 0
	s_cbranch_vccnz .LBB0_1796
	v_add_u32_e32 v18, s19, v17
	v_ashrrev_i32_e32 v19, 31, v18
	v_lshlrev_b64 v[18:19], 12, v[18:19]
	v_lshl_add_u64 v[18:19], v[10:11], 0, v[18:19]
	s_and_b32 s32, s20, 0xfff
	s_cbranch_scc1 .Ltc_skip7
	s_mov_b64 s[100:101], 0x4000
	v_mov_b64_e32 v[116:117], v[18:19]
	global_load_dword v100, v[116:117], off
	v_lshl_add_u64 v[116:117], v[116:117], 0, s[100:101]
	global_load_dword v101, v[116:117], off
	v_lshl_add_u64 v[116:117], v[116:117], 0, s[100:101]
	global_load_dword v102, v[116:117], off
	v_lshl_add_u64 v[116:117], v[116:117], 0, s[100:101]
	global_load_dword v103, v[116:117], off
	v_lshl_add_u64 v[116:117], v[116:117], 0, s[100:101]
	global_load_dword v104, v[116:117], off
	v_lshl_add_u64 v[116:117], v[116:117], 0, s[100:101]
	global_load_dword v105, v[116:117], off
	v_lshl_add_u64 v[116:117], v[116:117], 0, s[100:101]
	global_load_dword v106, v[116:117], off
	v_lshl_add_u64 v[116:117], v[116:117], 0, s[100:101]
	global_load_dword v107, v[116:117], off
	v_lshl_add_u64 v[116:117], v[116:117], 0, s[100:101]
	global_load_dword v108, v[116:117], off
	v_lshl_add_u64 v[116:117], v[116:117], 0, s[100:101]
	global_load_dword v109, v[116:117], off
	v_lshl_add_u64 v[116:117], v[116:117], 0, s[100:101]
	global_load_dword v110, v[116:117], off
	v_lshl_add_u64 v[116:117], v[116:117], 0, s[100:101]
	global_load_dword v111, v[116:117], off
	v_lshl_add_u64 v[116:117], v[116:117], 0, s[100:101]
	global_load_dword v112, v[116:117], off
	v_lshl_add_u64 v[116:117], v[116:117], 0, s[100:101]
	global_load_dword v113, v[116:117], off
	v_lshl_add_u64 v[116:117], v[116:117], 0, s[100:101]
	global_load_dword v114, v[116:117], off
	v_lshl_add_u64 v[116:117], v[116:117], 0, s[100:101]
	global_load_dword v115, v[116:117], off
	s_waitcnt vmcnt(0)

;     ...
;     for (int i = 0; i < 16; ++i) {
;       int e = tid + 256 * i, r = e >> 6, c = e & 63;
;       int n = nt * 64 + c;
;       int sc = remap ? colmap_in(n) : n;
;       float v = sc >= 0 ? src[(size_t)(kt * 64 + r) * Nsrc + sc] : 0.f;
;       tile[r * 65 + c] = v;
.LBB0_1796:
	v_mad_u64_u32 v[20:21], s[22:23], v17, s36, v[2:3]
	v_add_u32_e32 v17, 0x100, v0
	s_and_b64 vcc, exec, s[0:1]
	v_ashrrev_i32_e32 v17, 6, v17
	s_waitcnt vmcnt(0)
	ds_write_b32 v20, v18
	s_cbranch_vccnz .LBB0_1798
	v_add_u32_e32 v18, s19, v17
	v_ashrrev_i32_e32 v19, 31, v18
	v_lshlrev_b64 v[18:19], 12, v[18:19]
	v_lshl_add_u64 v[18:19], v[10:11], 0, v[18:19]
	v_mov_b32_e32 v16, v101
.LBB0_1798:
	v_mad_u64_u32 v[18:19], s[22:23], v17, s36, v[2:3]
	s_waitcnt vmcnt(0)
	ds_write_b32 v18, v16
	v_add_u32_e32 v16, 0x200, v0
	v_ashrrev_i32_e32 v17, 6, v16
	v_mov_b32_e32 v16, 0
	s_and_b64 vcc, exec, s[0:1]
	v_mov_b32_e32 v18, 0
	s_cbranch_vccnz .LBB0_1800
	v_add_u32_e32 v18, s19, v17
	v_ashrrev_i32_e32 v19, 31, v18
	v_lshlrev_b64 v[18:19], 12, v[18:19]
	v_lshl_add_u64 v[18:19], v[10:11], 0, v[18:19]
	v_mov_b32_e32 v18, v102
.LBB0_1800:
	v_add_u32_e32 v0, 0x300, v0
	v_mad_u64_u32 v[20:21], s[22:23], v17, s36, v[2:3]
	s_and_b64 vcc, exec, s[0:1]
	v_ashrrev_i32_e32 v0, 6, v0
	s_waitcnt vmcnt(0)
	ds_write_b32 v20, v18
	s_cbranch_vccnz .LBB0_1793
	v_add_u32_e32 v16, s19, v0
	v_ashrrev_i32_e32 v17, 31, v16
	v_lshlrev_b64 v[16:17], 12, v[16:17]
	v_lshl_add_u64 v[16:17], v[10:11], 0, v[16:17]
	v_mov_b32_e32 v16, v103
	v_mov_b32_e32 v100, v104
	v_mov_b32_e32 v101, v105
	v_mov_b32_e32 v102, v106
	v_mov_b32_e32 v103, v107
	v_mov_b32_e32 v104, v108
	v_mov_b32_e32 v105, v109
	v_mov_b32_e32 v106, v110
	v_mov_b32_e32 v107, v111
	v_mov_b32_e32 v108, v112
	v_mov_b32_e32 v109, v113
	v_mov_b32_e32 v110, v114
	v_mov_b32_e32 v111, v115
	s_branch .LBB0_1793

;     ...
;   for (int t = blockIdx.x; t < ntiles; t += gridDim.x) {
;     const int kt = t % nkt, nt = t / nkt;
;     __syncthreads();
; #pragma unroll 4
;     for (int i = 0; i < 16; ++i) {
;       int e = tid + 256 * i, r = e >> 6, c = e & 63;
;       int n = nt * 64 + c;
;       int sc = remap ? colmap_in(n) : n;
;       float v = sc >= 0 ? src[(size_t)(kt * 64 + r) * Nsrc + sc] : 0.f;
;       tile[r * 65 + c] = v;
.LBB0_1820:
	v_add_u32_e32 v0, s22, v3
	v_cndmask_b32_e64 v18, 0, 1, s[18:19]
	v_ashrrev_i32_e32 v17, 6, v0
	v_mov_b32_e32 v16, 0
	v_cmp_ne_u32_e64 s[0:1], 1, v18
	s_andn2_b64 vcc, exec, s[18:19]
	v_mov_b32_e32 v18, 0
	s_cbranch_vccnz .LBB0_1822
	v_add_u32_e32 v18, s21, v17
	v_ashrrev_i32_e32 v19, 31, v18
	v_lshlrev_b64 v[18:19], 12, v[18:19]
	v_lshl_add_u64 v[18:19], v[10:11], 0, v[18:19]
	s_and_b32 s32, s22, 0xfff
	s_cbranch_scc1 .Ltc_skip5
	s_mov_b64 s[100:101], 0x4000
	v_mov_b64_e32 v[116:117], v[18:19]
	global_load_dword v100, v[116:117], off
	v_lshl_add_u64 v[116:117], v[116:117], 0, s[100:101]
	global_load_dword v101, v[116:117], off
	v_lshl_add_u64 v[116:117], v[116:117], 0, s[100:101]
	global_load_dword v102, v[116:117], off
	v_lshl_add_u64 v[116:117], v[116:117], 0, s[100:101]
	global_load_dword v103, v[116:117], off
	v_lshl_add_u64 v[116:117], v[116:117], 0, s[100:101]
	global_load_dword v104, v[116:117], off
	v_lshl_add_u64 v[116:117], v[116:117], 0, s[100:101]
	global_load_dword v105, v[116:117], off
	v_lshl_add_u64 v[116:117], v[116:117], 0, s[100:101]
	global_load_dword v106, v[116:117], off
	v_lshl_add_u64 v[116:117], v[116:117], 0, s[100:101]
	global_load_dword v107, v[116:117], off
	v_lshl_add_u64 v[116:117], v[116:117], 0, s[100:101]
	global_load_dword v108, v[116:117], off
	v_lshl_add_u64 v[116:117], v[116:117], 0, s[100:101]
	global_load_dword v109, v[116:117], off
	v_lshl_add_u64 v[116:117], v[116:117], 0, s[100:101]
	global_load_dword v110, v[116:117], off
	v_lshl_add_u64 v[116:117], v[116:117], 0, s[100:101]
	global_load_dword v111, v[116:117], off
	v_lshl_add_u64 v[116:117], v[116:117], 0, s[100:101]
	global_load_dword v112, v[116:117], off
	v_lshl_add_u64 v[116:117], v[116:117], 0, s[100:101]
	global_load_dword v113, v[116:117], off
	v_lshl_add_u64 v[116:117], v[116:117], 0, s[100:101]
	global_load_dword v114, v[116:117], off
	v_lshl_add_u64 v[116:117], v[116:117], 0, s[100:101]
	global_load_dword v115, v[116:117], off
	s_waitcnt vmcnt(0)

;     ...
;     for (int i = 0; i < 16; ++i) {
;       int e = tid + 256 * i, r = e >> 6, c = e & 63;
;       int n = nt * 64 + c;
;       int sc = remap ? colmap_in(n) : n;
;       float v = sc >= 0 ? src[(size_t)(kt * 64 + r) * Nsrc + sc] : 0.f;
;       tile[r * 65 + c] = v;
.LBB0_1822:
	v_mad_u64_u32 v[20:21], s[24:25], v17, s36, v[2:3]
	v_add_u32_e32 v17, 0x100, v0
	s_and_b64 vcc, exec, s[0:1]
	v_ashrrev_i32_e32 v17, 6, v17
	s_waitcnt vmcnt(0)
	ds_write_b32 v20, v18
	s_cbranch_vccnz .LBB0_1824
	v_add_u32_e32 v18, s21, v17
	v_ashrrev_i32_e32 v19, 31, v18
	v_lshlrev_b64 v[18:19], 12, v[18:19]
	v_lshl_add_u64 v[18:19], v[10:11], 0, v[18:19]
	v_mov_b32_e32 v16, v101
.LBB0_1824:
	v_mad_u64_u32 v[18:19], s[24:25], v17, s36, v[2:3]
	s_waitcnt vmcnt(0)
	ds_write_b32 v18, v16
	v_add_u32_e32 v16, 0x200, v0
	v_ashrrev_i32_e32 v17, 6, v16
	v_mov_b32_e32 v16, 0
	s_and_b64 vcc, exec, s[0:1]
	v_mov_b32_e32 v18, 0
	s_cbranch_vccnz .LBB0_1826
	v_add_u32_e32 v18, s21, v17
	v_ashrrev_i32_e32 v19, 31, v18
	v_lshlrev_b64 v[18:19], 12, v[18:19]
	v_lshl_add_u64 v[18:19], v[10:11], 0, v[18:19]
	v_mov_b32_e32 v18, v102
.LBB0_1826:
	v_add_u32_e32 v0, 0x300, v0
	v_mad_u64_u32 v[20:21], s[24:25], v17, s36, v[2:3]
	s_and_b64 vcc, exec, s[0:1]
	v_ashrrev_i32_e32 v0, 6, v0
	s_waitcnt vmcnt(0)
	ds_write_b32 v20, v18
	s_cbranch_vccnz .LBB0_1819
	v_add_u32_e32 v16, s21, v0
	v_ashrrev_i32_e32 v17, 31, v16
	v_lshlrev_b64 v[16:17], 12, v[16:17]
	v_lshl_add_u64 v[16:17], v[10:11], 0, v[16:17]
	v_mov_b32_e32 v16, v103
	v_mov_b32_e32 v100, v104
	v_mov_b32_e32 v101, v105
	v_mov_b32_e32 v102, v106
	v_mov_b32_e32 v103, v107
	v_mov_b32_e32 v104, v108
	v_mov_b32_e32 v105, v109
	v_mov_b32_e32 v106, v110
	v_mov_b32_e32 v107, v111
	v_mov_b32_e32 v108, v112
	v_mov_b32_e32 v109, v113
	v_mov_b32_e32 v110, v114
	v_mov_b32_e32 v111, v115
	s_branch .LBB0_1819

;     ...
;   for (int t = blockIdx.x; t < ntiles; t += gridDim.x) {
;     const int kt = t % nkt, nt = t / nkt;
;     __syncthreads();
; #pragma unroll 4
;     for (int i = 0; i < 16; ++i) {
;       int e = tid + 256 * i, r = e >> 6, c = e & 63;
;       int n = nt * 64 + c;
;       int sc = remap ? colmap_in(n) : n;
;       float v = sc >= 0 ? src[(size_t)(kt * 64 + r) * Nsrc + sc] : 0.f;
;       tile[r * 65 + c] = v;
.LBB0_1833:
	v_add_u32_e32 v0, s20, v3
	v_cndmask_b32_e64 v18, 0, 1, s[12:13]
	v_ashrrev_i32_e32 v17, 6, v0
	v_mov_b32_e32 v16, 0
	v_cmp_ne_u32_e64 s[0:1], 1, v18
	s_andn2_b64 vcc, exec, s[12:13]
	v_mov_b32_e32 v18, 0
	s_cbranch_vccnz .LBB0_1835
	v_add_u32_e32 v18, s19, v17
	v_ashrrev_i32_e32 v19, 31, v18
	v_lshlrev_b64 v[18:19], 12, v[18:19]
	v_lshl_add_u64 v[18:19], v[10:11], 0, v[18:19]
	s_and_b32 s32, s20, 0xfff
	s_cbranch_scc1 .Ltc_skip4
	s_mov_b64 s[100:101], 0x4000
	v_mov_b64_e32 v[116:117], v[18:19]
	global_load_dword v100, v[116:117], off
	v_lshl_add_u64 v[116:117], v[116:117], 0, s[100:101]
	global_load_dword v101, v[116:117], off
	v_lshl_add_u64 v[116:117], v[116:117], 0, s[100:101]
	global_load_dword v102, v[116:117], off
	v_lshl_add_u64 v[116:117], v[116:117], 0, s[100:101]
	global_load_dword v103, v[116:117], off
	v_lshl_add_u64 v[116:117], v[116:117], 0, s[100:101]
	global_load_dword v104, v[116:117], off
	v_lshl_add_u64 v[116:117], v[116:117], 0, s[100:101]
	global_load_dword v105, v[116:117], off
	v_lshl_add_u64 v[116:117], v[116:117], 0, s[100:101]
	global_load_dword v106, v[116:117], off
	v_lshl_add_u64 v[116:117], v[116:117], 0, s[100:101]
	global_load_dword v107, v[116:117], off
	v_lshl_add_u64 v[116:117], v[116:117], 0, s[100:101]
	global_load_dword v108, v[116:117], off
	v_lshl_add_u64 v[116:117], v[116:117], 0, s[100:101]
	global_load_dword v109, v[116:117], off
	v_lshl_add_u64 v[116:117], v[116:117], 0, s[100:101]
	global_load_dword v110, v[116:117], off
	v_lshl_add_u64 v[116:117], v[116:117], 0, s[100:101]
	global_load_dword v111, v[116:117], off
	v_lshl_add_u64 v[116:117], v[116:117], 0, s[100:101]
	global_load_dword v112, v[116:117], off
	v_lshl_add_u64 v[116:117], v[116:117], 0, s[100:101]
	global_load_dword v113, v[116:117], off
	v_lshl_add_u64 v[116:117], v[116:117], 0, s[100:101]
	global_load_dword v114, v[116:117], off
	v_lshl_add_u64 v[116:117], v[116:117], 0, s[100:101]
	global_load_dword v115, v[116:117], off
	s_waitcnt vmcnt(0)

;     ...
;   for (int t = blockIdx.x; t < ntiles; t += gridDim.x) {
;     const int kt = t % nkt, nt = t / nkt;
;     __syncthreads();
; #pragma unroll 4
;     for (int i = 0; i < 16; ++i) {
;       int e = tid + 256 * i, r = e >> 6, c = e & 63;
;       int n = nt * 64 + c;
;       int sc = remap ? colmap_in(n) : n;
;       float v = sc >= 0 ? src[(size_t)(kt * 64 + r) * Nsrc + sc] : 0.f;
;       tile[r * 65 + c] = v;
.LBB0_1846:
	v_add_u32_e32 v0, s18, v3
	v_cndmask_b32_e64 v18, 0, 1, s[14:15]
	v_ashrrev_i32_e32 v17, 6, v0
	v_mov_b32_e32 v16, 0
	v_cmp_ne_u32_e64 s[0:1], 1, v18
	s_andn2_b64 vcc, exec, s[14:15]
	v_mov_b32_e32 v18, 0
	s_cbranch_vccnz .LBB0_1848
	v_add_u32_e32 v18, s17, v17
	v_ashrrev_i32_e32 v19, 31, v18
	v_lshlrev_b64 v[18:19], 12, v[18:19]
	v_lshl_add_u64 v[18:19], v[10:11], 0, v[18:19]
	s_and_b32 s32, s18, 0xfff
	s_cbranch_scc1 .Ltc_skip3
	s_mov_b64 s[100:101], 0x4000
	v_mov_b64_e32 v[116:117], v[18:19]
	global_load_dword v100, v[116:117], off
	v_lshl_add_u64 v[116:117], v[116:117], 0, s[100:101]
	global_load_dword v101, v[116:117], off
	v_lshl_add_u64 v[116:117], v[116:117], 0, s[100:101]
	global_load_dword v102, v[116:117], off
	v_lshl_add_u64 v[116:117], v[116:117], 0, s[100:101]
	global_load_dword v103, v[116:117], off
	v_lshl_add_u64 v[116:117], v[116:117], 0, s[100:101]
	global_load_dword v104, v[116:117], off
	v_lshl_add_u64 v[116:117], v[116:117], 0, s[100:101]
	global_load_dword v105, v[116:117], off
	v_lshl_add_u64 v[116:117], v[116:117], 0, s[100:101]
	global_load_dword v106, v[116:117], off
	v_lshl_add_u64 v[116:117], v[116:117], 0, s[100:101]
	global_load_dword v107, v[116:117], off
	v_lshl_add_u64 v[116:117], v[116:117], 0, s[100:101]
	global_load_dword v108, v[116:117], off
	v_lshl_add_u64 v[116:117], v[116:117], 0, s[100:101]
	global_load_dword v109, v[116:117], off
	v_lshl_add_u64 v[116:117], v[116:117], 0, s[100:101]
	global_load_dword v110, v[116:117], off
	v_lshl_add_u64 v[116:117], v[116:117], 0, s[100:101]
	global_load_dword v111, v[116:117], off
	v_lshl_add_u64 v[116:117], v[116:117], 0, s[100:101]
	global_load_dword v112, v[116:117], off
	v_lshl_add_u64 v[116:117], v[116:117], 0, s[100:101]
	global_load_dword v113, v[116:117], off
	v_lshl_add_u64 v[116:117], v[116:117], 0, s[100:101]
	global_load_dword v114, v[116:117], off
	v_lshl_add_u64 v[116:117], v[116:117], 0, s[100:101]
	global_load_dword v115, v[116:117], off
	s_waitcnt vmcnt(0)

;     ...
;     for (int i = 0; i < 16; ++i) {
;       int e = tid + 256 * i, r = e >> 6, c = e & 63;
;       int n = nt * 64 + c;
;       int sc = remap ? colmap_in(n) : n;
;       float v = sc >= 0 ? src[(size_t)(kt * 64 + r) * Nsrc + sc] : 0.f;
;       tile[r * 65 + c] = v;
.LBB0_1848:
	v_mad_u64_u32 v[20:21], s[20:21], v17, s36, v[2:3]
	v_add_u32_e32 v17, 0x100, v0
	s_and_b64 vcc, exec, s[0:1]
	v_ashrrev_i32_e32 v17, 6, v17
	s_waitcnt vmcnt(0)
	ds_write_b32 v20, v18
	s_cbranch_vccnz .LBB0_1850
	v_add_u32_e32 v18, s17, v17
	v_ashrrev_i32_e32 v19, 31, v18
	v_lshlrev_b64 v[18:19], 12, v[18:19]
	v_lshl_add_u64 v[18:19], v[10:11], 0, v[18:19]
	v_mov_b32_e32 v16, v101
.LBB0_1850:
	v_mad_u64_u32 v[18:19], s[20:21], v17, s36, v[2:3]
	s_waitcnt vmcnt(0)
	ds_write_b32 v18, v16
	v_add_u32_e32 v16, 0x200, v0
	v_ashrrev_i32_e32 v17, 6, v16
	v_mov_b32_e32 v16, 0
	s_and_b64 vcc, exec, s[0:1]
	v_mov_b32_e32 v18, 0
	s_cbranch_vccnz .LBB0_1852
	v_add_u32_e32 v18, s17, v17
	v_ashrrev_i32_e32 v19, 31, v18
	v_lshlrev_b64 v[18:19], 12, v[18:19]
	v_lshl_add_u64 v[18:19], v[10:11], 0, v[18:19]
	v_mov_b32_e32 v18, v102
.LBB0_1852:
	v_add_u32_e32 v0, 0x300, v0
	v_mad_u64_u32 v[20:21], s[20:21], v17, s36, v[2:3]
	s_and_b64 vcc, exec, s[0:1]
	v_ashrrev_i32_e32 v0, 6, v0
	s_waitcnt vmcnt(0)
	ds_write_b32 v20, v18
	s_cbranch_vccnz .LBB0_1845
	v_add_u32_e32 v16, s17, v0
	v_ashrrev_i32_e32 v17, 31, v16
	v_lshlrev_b64 v[16:17], 12, v[16:17]
	v_lshl_add_u64 v[16:17], v[10:11], 0, v[16:17]
	v_mov_b32_e32 v16, v103
	v_mov_b32_e32 v100, v104
	v_mov_b32_e32 v101, v105
	v_mov_b32_e32 v102, v106
	v_mov_b32_e32 v103, v107
	v_mov_b32_e32 v104, v108
	v_mov_b32_e32 v105, v109
	v_mov_b32_e32 v106, v110
	v_mov_b32_e32 v107, v111
	v_mov_b32_e32 v108, v112
	v_mov_b32_e32 v109, v113
	v_mov_b32_e32 v110, v114
	v_mov_b32_e32 v111, v115
	s_branch .LBB0_1845

;     ...
;   for (int t = blockIdx.x; t < ntiles; t += gridDim.x) {
;     const int kt = t % nkt, nt = t / nkt;
;     __syncthreads();
; #pragma unroll 4
;     for (int i = 0; i < 16; ++i) {
;       int e = tid + 256 * i, r = e >> 6, c = e & 63;
;       int n = nt * 64 + c;
;       int sc = remap ? colmap_in(n) : n;
;       float v = sc >= 0 ? src[(size_t)(kt * 64 + r) * Nsrc + sc] : 0.f;
;       tile[r * 65 + c] = v;
.LBB0_1859:
	v_add_u32_e32 v0, s20, v3
	v_cndmask_b32_e64 v18, 0, 1, s[16:17]
	v_ashrrev_i32_e32 v17, 6, v0
	v_mov_b32_e32 v16, 0
	v_cmp_ne_u32_e64 s[0:1], 1, v18
	s_andn2_b64 vcc, exec, s[16:17]
	v_mov_b32_e32 v18, 0
	s_cbranch_vccnz .LBB0_1861
	v_add_u32_e32 v18, s19, v17
	v_ashrrev_i32_e32 v19, 31, v18
	v_lshlrev_b64 v[18:19], 14, v[18:19]
	v_lshl_add_u64 v[18:19], v[10:11], 0, v[18:19]
	s_and_b32 s32, s20, 0xfff
	s_cbranch_scc1 .Ltc_skip2
	s_mov_b64 s[100:101], 0x10000
	v_mov_b64_e32 v[116:117], v[18:19]
	global_load_dword v100, v[116:117], off
	v_lshl_add_u64 v[116:117], v[116:117], 0, s[100:101]
	global_load_dword v101, v[116:117], off
	v_lshl_add_u64 v[116:117], v[116:117], 0, s[100:101]
	global_load_dword v102, v[116:117], off
	v_lshl_add_u64 v[116:117], v[116:117], 0, s[100:101]
	global_load_dword v103, v[116:117], off
	v_lshl_add_u64 v[116:117], v[116:117], 0, s[100:101]
	global_load_dword v104, v[116:117], off
	v_lshl_add_u64 v[116:117], v[116:117], 0, s[100:101]
	global_load_dword v105, v[116:117], off
	v_lshl_add_u64 v[116:117], v[116:117], 0, s[100:101]
	global_load_dword v106, v[116:117], off
	v_lshl_add_u64 v[116:117], v[116:117], 0, s[100:101]
	global_load_dword v107, v[116:117], off
	v_lshl_add_u64 v[116:117], v[116:117], 0, s[100:101]
	global_load_dword v108, v[116:117], off
	v_lshl_add_u64 v[116:117], v[116:117], 0, s[100:101]
	global_load_dword v109, v[116:117], off
	v_lshl_add_u64 v[116:117], v[116:117], 0, s[100:101]
	global_load_dword v110, v[116:117], off
	v_lshl_add_u64 v[116:117], v[116:117], 0, s[100:101]
	global_load_dword v111, v[116:117], off
	v_lshl_add_u64 v[116:117], v[116:117], 0, s[100:101]
	global_load_dword v112, v[116:117], off
	v_lshl_add_u64 v[116:117], v[116:117], 0, s[100:101]
	global_load_dword v113, v[116:117], off
	v_lshl_add_u64 v[116:117], v[116:117], 0, s[100:101]
	global_load_dword v114, v[116:117], off
	v_lshl_add_u64 v[116:117], v[116:117], 0, s[100:101]
	global_load_dword v115, v[116:117], off
	s_waitcnt vmcnt(0)

;     ...
;     for (int i = 0; i < 16; ++i) {
;       int e = tid + 256 * i, r = e >> 6, c = e & 63;
;       int n = nt * 64 + c;
;       int sc = remap ? colmap_in(n) : n;
;       float v = sc >= 0 ? src[(size_t)(kt * 64 + r) * Nsrc + sc] : 0.f;
;       tile[r * 65 + c] = v;
.LBB0_1861:
	v_mad_u64_u32 v[20:21], s[22:23], v17, s36, v[2:3]
	v_add_u32_e32 v17, 0x100, v0
	s_and_b64 vcc, exec, s[0:1]
	v_ashrrev_i32_e32 v17, 6, v17
	s_waitcnt vmcnt(0)
	ds_write_b32 v20, v18
	s_cbranch_vccnz .LBB0_1863
	v_add_u32_e32 v18, s19, v17
	v_ashrrev_i32_e32 v19, 31, v18
	v_lshlrev_b64 v[18:19], 14, v[18:19]
	v_lshl_add_u64 v[18:19], v[10:11], 0, v[18:19]
	v_mov_b32_e32 v16, v101
.LBB0_1863:
	v_mad_u64_u32 v[18:19], s[22:23], v17, s36, v[2:3]
	s_waitcnt vmcnt(0)
	ds_write_b32 v18, v16
	v_add_u32_e32 v16, 0x200, v0
	v_ashrrev_i32_e32 v17, 6, v16
	v_mov_b32_e32 v16, 0
	s_and_b64 vcc, exec, s[0:1]
	v_mov_b32_e32 v18, 0
	s_cbranch_vccnz .LBB0_1865
	v_add_u32_e32 v18, s19, v17
	v_ashrrev_i32_e32 v19, 31, v18
	v_lshlrev_b64 v[18:19], 14, v[18:19]
	v_lshl_add_u64 v[18:19], v[10:11], 0, v[18:19]
	v_mov_b32_e32 v18, v102
.LBB0_1865:
	v_add_u32_e32 v0, 0x300, v0
	v_mad_u64_u32 v[20:21], s[22:23], v17, s36, v[2:3]
	s_and_b64 vcc, exec, s[0:1]
	v_ashrrev_i32_e32 v0, 6, v0
	s_waitcnt vmcnt(0)
	ds_write_b32 v20, v18
	s_cbranch_vccnz .LBB0_1858
	v_add_u32_e32 v16, s19, v0
	v_ashrrev_i32_e32 v17, 31, v16
	v_lshlrev_b64 v[16:17], 14, v[16:17]
	v_lshl_add_u64 v[16:17], v[10:11], 0, v[16:17]
	v_mov_b32_e32 v16, v103
	v_mov_b32_e32 v100, v104
	v_mov_b32_e32 v101, v105
	v_mov_b32_e32 v102, v106
	v_mov_b32_e32 v103, v107
	v_mov_b32_e32 v104, v108
	v_mov_b32_e32 v105, v109
	v_mov_b32_e32 v106, v110
	v_mov_b32_e32 v107, v111
	v_mov_b32_e32 v108, v112
	v_mov_b32_e32 v109, v113
	v_mov_b32_e32 v110, v114
	v_mov_b32_e32 v111, v115
	s_branch .LBB0_1858

;     ...
;   for (int t = blockIdx.x; t < ntiles; t += gridDim.x) {
;     const int kt = t % nkt, nt = t / nkt;
;     __syncthreads();
; #pragma unroll 4
;     for (int i = 0; i < 16; ++i) {
;       int e = tid + 256 * i, r = e >> 6, c = e & 63;
;       int n = nt * 64 + c;
;       int sc = remap ? colmap_in(n) : n;
;       float v = sc >= 0 ? src[(size_t)(kt * 64 + r) * Nsrc + sc] : 0.f;
;       tile[r * 65 + c] = v;
.LBB0_1872:
	v_add_u32_e32 v0, s14, v3
	v_cndmask_b32_e64 v18, 0, 1, s[10:11]
	v_ashrrev_i32_e32 v17, 6, v0
	v_mov_b32_e32 v16, 0
	v_cmp_ne_u32_e64 s[0:1], 1, v18
	s_andn2_b64 vcc, exec, s[10:11]
	v_mov_b32_e32 v18, 0
	s_cbranch_vccnz .LBB0_1874
	v_add_u32_e32 v18, s13, v17
	v_ashrrev_i32_e32 v19, 31, v18
	v_lshlrev_b64 v[18:19], 12, v[18:19]
	v_lshl_add_u64 v[18:19], v[10:11], 0, v[18:19]
	s_and_b32 s32, s14, 0xfff
	s_cbranch_scc1 .Ltc_skip1
	s_mov_b64 s[100:101], 0x4000
	v_mov_b64_e32 v[116:117], v[18:19]
	global_load_dword v100, v[116:117], off
	v_lshl_add_u64 v[116:117], v[116:117], 0, s[100:101]
	global_load_dword v101, v[116:117], off
	v_lshl_add_u64 v[116:117], v[116:117], 0, s[100:101]
	global_load_dword v102, v[116:117], off
	v_lshl_add_u64 v[116:117], v[116:117], 0, s[100:101]
	global_load_dword v103, v[116:117], off
	v_lshl_add_u64 v[116:117], v[116:117], 0, s[100:101]
	global_load_dword v104, v[116:117], off
	v_lshl_add_u64 v[116:117], v[116:117], 0, s[100:101]
	global_load_dword v105, v[116:117], off
	v_lshl_add_u64 v[116:117], v[116:117], 0, s[100:101]
	global_load_dword v106, v[116:117], off
	v_lshl_add_u64 v[116:117], v[116:117], 0, s[100:101]
	global_load_dword v107, v[116:117], off
	v_lshl_add_u64 v[116:117], v[116:117], 0, s[100:101]
	global_load_dword v108, v[116:117], off
	v_lshl_add_u64 v[116:117], v[116:117], 0, s[100:101]
	global_load_dword v109, v[116:117], off
	v_lshl_add_u64 v[116:117], v[116:117], 0, s[100:101]
	global_load_dword v110, v[116:117], off
	v_lshl_add_u64 v[116:117], v[116:117], 0, s[100:101]
	global_load_dword v111, v[116:117], off
	v_lshl_add_u64 v[116:117], v[116:117], 0, s[100:101]
	global_load_dword v112, v[116:117], off
	v_lshl_add_u64 v[116:117], v[116:117], 0, s[100:101]
	global_load_dword v113, v[116:117], off
	v_lshl_add_u64 v[116:117], v[116:117], 0, s[100:101]
	global_load_dword v114, v[116:117], off
	v_lshl_add_u64 v[116:117], v[116:117], 0, s[100:101]
	global_load_dword v115, v[116:117], off
	s_waitcnt vmcnt(0)

;     ...
;     for (int i = 0; i < 16; ++i) {
;       int e = tid + 256 * i, r = e >> 6, c = e & 63;
;       int n = nt * 64 + c;
;       int sc = remap ? colmap_in(n) : n;
;       float v = sc >= 0 ? src[(size_t)(kt * 64 + r) * Nsrc + sc] : 0.f;
;       tile[r * 65 + c] = v;
.LBB0_1874:
	v_mad_u64_u32 v[20:21], s[16:17], v17, s36, v[2:3]
	v_add_u32_e32 v17, 0x100, v0
	s_and_b64 vcc, exec, s[0:1]
	v_ashrrev_i32_e32 v17, 6, v17
	s_waitcnt vmcnt(0)
	ds_write_b32 v20, v18
	s_cbranch_vccnz .LBB0_1876
	v_add_u32_e32 v18, s13, v17
	v_ashrrev_i32_e32 v19, 31, v18
	v_lshlrev_b64 v[18:19], 12, v[18:19]
	v_lshl_add_u64 v[18:19], v[10:11], 0, v[18:19]
	v_mov_b32_e32 v16, v101
.LBB0_1876:
	v_mad_u64_u32 v[18:19], s[16:17], v17, s36, v[2:3]
	s_waitcnt vmcnt(0)
	ds_write_b32 v18, v16
	v_add_u32_e32 v16, 0x200, v0
	v_ashrrev_i32_e32 v17, 6, v16
	v_mov_b32_e32 v16, 0
	s_and_b64 vcc, exec, s[0:1]
	v_mov_b32_e32 v18, 0
	s_cbranch_vccnz .LBB0_1878
	v_add_u32_e32 v18, s13, v17
	v_ashrrev_i32_e32 v19, 31, v18
	v_lshlrev_b64 v[18:19], 12, v[18:19]
	v_lshl_add_u64 v[18:19], v[10:11], 0, v[18:19]
	v_mov_b32_e32 v18, v102
.LBB0_1878:
	v_add_u32_e32 v0, 0x300, v0
	v_mad_u64_u32 v[20:21], s[16:17], v17, s36, v[2:3]
	s_and_b64 vcc, exec, s[0:1]
	v_ashrrev_i32_e32 v0, 6, v0
	s_waitcnt vmcnt(0)
	ds_write_b32 v20, v18
	s_cbranch_vccnz .LBB0_1871
	v_add_u32_e32 v16, s13, v0
	v_ashrrev_i32_e32 v17, 31, v16
	v_lshlrev_b64 v[16:17], 12, v[16:17]
	v_lshl_add_u64 v[16:17], v[10:11], 0, v[16:17]
	v_mov_b32_e32 v16, v103
	v_mov_b32_e32 v100, v104
	v_mov_b32_e32 v101, v105
	v_mov_b32_e32 v102, v106
	v_mov_b32_e32 v103, v107
	v_mov_b32_e32 v104, v108
	v_mov_b32_e32 v105, v109
	v_mov_b32_e32 v106, v110
	v_mov_b32_e32 v107, v111
	v_mov_b32_e32 v108, v112
	v_mov_b32_e32 v109, v113
	v_mov_b32_e32 v110, v114
	v_mov_b32_e32 v111, v115
	s_branch .LBB0_1871
